# v91 + GEMM epilogues: packed f32 VALU split into scalar halves (672 sites) to test the packed-op cost outside MFMA gaps
# baseline (speedup 1.0000x reference)
; __device__ __forceinline__ void load_rstd(const float* ssq, int row0, int fq, float (&rs)[2][4]) {
; #pragma unroll
;     for (int ai = 0; ai < 2; ++ai)
; #pragma unroll
;         for (int m = 0; m < 4; ++m) {
;             const f32x4 v = *(const f32x4*)(ssq + (size_t)(row0 + ai * HALF + m * 16) * 16 + 4 * fq);
;             float s = (v[0] + v[1]) + (v[2] + v[3]);
;             s += shx<16>(s); s += shx<32>(s);
;             rs[ai][m] = rsqrtf(s * (1.0f / 1024.0f) + RMS_EPS_F);
;         }
;     __device__ __forceinline__ void operator()(const f32x4 (&acc)[2][2][4][2], const Unit& u, int wr, int wc, int fr, int fq) const {
;         const int buf = u.pn >> 2, pl = u.pn & 3;
;         const int row0 = u.pm * BM + wr * 64 + fr;
;         const int colbase = 256 * pl + 64 * wc + 8 * fq;
;         bf16_t* base = Q + (size_t)buf * (size_t)(32u << 20);
;         const bool norm = (buf < 2) && (odd || pl >= 2);
;         const float sc = (buf == 0) ? C2_F : 1.0f;
;         const float* g = gq + ((buf == 0) ? 0 : (gk - gq));
;         const f32x4 one4 = (f32x4){1.f, 1.f, 1.f, 1.f};
;         const float* gp = g + 8 * fq;
;         const f32x4 g00 = (norm ? *(const f32x4*)(gp) : one4) * sc, g01 = (norm ? *(const f32x4*)(gp + 4) : one4) * sc;
;         const f32x4 g10 = (norm ? *(const f32x4*)(gp + 32) : one4) * sc, g11 = (norm ? *(const f32x4*)(gp + 36) : one4) * sc;
;         float rs[2][4]; load_rstd(ssq, row0, fq, rs);
.Lqe_g1:
	v_lshlrev_b32_e32 v192, 6, v202
	v_mov_b32_e32 v193, v2
	v_lshl_add_u64 v[194:195], v[176:177], 0, v[192:193]
	s_mov_b32 s100, 0x2000
	s_mov_b32 s101, 0
	v_lshl_add_u64 v[198:199], v[194:195], 0, s[100:101]
	global_load_dwordx4 v[148:151], v[194:195], off
	global_load_dwordx4 v[152:155], v[194:195], off offset:1024
	global_load_dwordx4 v[156:159], v[194:195], off offset:2048
	global_load_dwordx4 v[160:163], v[194:195], off offset:3072
	global_load_dwordx4 v[208:211], v[198:199], off
	global_load_dwordx4 v[212:215], v[198:199], off offset:1024
	global_load_dwordx4 v[216:219], v[198:199], off offset:2048
	global_load_dwordx4 v[220:223], v[198:199], off offset:3072
	v_lshl_or_b32 v192, s3, 9, v206
	v_lshl_add_u32 v192, v202, 11, v192
	v_lshl_add_u64 v[166:167], s[10:11], 0, v[192:193]
	s_waitcnt vmcnt(7)
	v_add_f32_e32 v182, v148, v149
	v_add_f32_e32 v150, v150, v151
	v_add_f32_e32 v182, v182, v150
	s_waitcnt vmcnt(6)
	v_add_f32_e32 v183, v152, v153
	v_add_f32_e32 v154, v154, v155
	v_add_f32_e32 v183, v183, v154
	s_waitcnt vmcnt(5)
	v_add_f32_e32 v184, v156, v157
	v_add_f32_e32 v158, v158, v159
	v_add_f32_e32 v184, v184, v158
	s_waitcnt vmcnt(4)
	v_add_f32_e32 v185, v160, v161
	v_add_f32_e32 v162, v162, v163
	v_add_f32_e32 v185, v185, v162
	s_waitcnt vmcnt(3)
	v_add_f32_e32 v186, v208, v209
	v_add_f32_e32 v210, v210, v211
	v_add_f32_e32 v186, v186, v210
	s_waitcnt vmcnt(2)
	v_add_f32_e32 v187, v212, v213
	v_add_f32_e32 v214, v214, v215
	v_add_f32_e32 v187, v187, v214
	s_waitcnt vmcnt(1)
	v_add_f32_e32 v188, v216, v217
	v_add_f32_e32 v218, v218, v219
	v_add_f32_e32 v188, v188, v218
	s_waitcnt vmcnt(0)
	v_add_f32_e32 v189, v220, v221
	v_add_f32_e32 v222, v222, v223
	v_add_f32_e32 v189, v189, v222
	s_nop 1
	v_permlane32_swap_b32_e32 v182, v183
	v_permlane32_swap_b32_e32 v184, v185
	v_permlane32_swap_b32_e32 v186, v187
	v_permlane32_swap_b32_e32 v188, v189
	v_add_f32_e32 v182, v182, v183
	v_add_f32_e32 v184, v184, v185
	v_add_f32_e32 v186, v186, v187
	v_add_f32_e32 v188, v188, v189
	s_nop 1
	v_permlane16_swap_b32_e32 v182, v184
	v_permlane16_swap_b32_e32 v186, v188
	v_add_f32_e32 v182, v182, v184
	v_add_f32_e32 v186, v186, v188
	v_fmamk_f32 v190, v182, 0x3a800000, v196
	v_fmamk_f32 v191, v186, 0x3a800000, v196
	v_rsq_f32_e32 v190, v190
	v_rsq_f32_e32 v191, v191
	s_and_b64 vcc, exec, s[30:31]
	s_cbranch_vccz .Lqe_nn
;     __device__ __forceinline__ void operator()(const f32x4 (&acc)[2][2][4][2], const Unit& u, int wr, int wc, int fr, int fq) const {
;     ...
;         const float sc = (buf == 0) ? C2_F : 1.0f;
;         const float* g = gq + ((buf == 0) ? 0 : (gk - gq));
;         const f32x4 one4 = (f32x4){1.f, 1.f, 1.f, 1.f};
;         const float* gp = g + 8 * fq;
;         const f32x4 g00 = (norm ? *(const f32x4*)(gp) : one4) * sc, g01 = (norm ? *(const f32x4*)(gp + 4) : one4) * sc;
;         const f32x4 g10 = (norm ? *(const f32x4*)(gp + 32) : one4) * sc, g11 = (norm ? *(const f32x4*)(gp + 36) : one4) * sc;
;     ...
;                 if (norm) {
;                     float ss = 0.f;
; #pragma unroll
;                     for (int bj = 0; bj < 2; ++bj)
; #pragma unroll
;                         for (int n = 0; n < 2; ++n) { const f32x4 x = acc[ai][bj][m][n]; ss += (x[0] * x[0] + x[1] * x[1]) + (x[2] * x[2] + x[3] * x[3]); }
;                     ss += shx<16>(ss); ss += shx<32>(ss);
;                     mul *= rsqrtf(ss * mul * mul * (1.0f / 64.0f) + RMS_EPS_F);
;                 }
	v_mov_b32_e32 v192, 0x3e38aa3b
	v_cndmask_b32_e64 v192, 1.0, v192, s[8:9]
	v_mul_f32_e32 v132, v192, v132
	v_mul_f32_e32 v133, v192, v133
	v_mul_f32_e32 v134, v192, v134
	v_mul_f32_e32 v135, v192, v135
	v_mul_f32_e32 v136, v192, v136
	v_mul_f32_e32 v137, v192, v137
	v_mul_f32_e32 v138, v192, v138
	v_mul_f32_e32 v139, v192, v139
	v_mul_f32_e32 v140, v192, v140
	v_mul_f32_e32 v141, v192, v141
	v_mul_f32_e32 v142, v192, v142
	v_mul_f32_e32 v143, v192, v143
	v_mul_f32_e32 v144, v192, v144
	v_mul_f32_e32 v145, v192, v145
	v_mul_f32_e32 v146, v192, v146
	v_mul_f32_e32 v147, v192, v147
	v_mul_f32_e32 v216, v128, v128
	v_mul_f32_e32 v217, v129, v129
	v_mul_f32_e32 v218, v130, v130
	v_mul_f32_e32 v219, v131, v131
	v_mul_f32_e32 v220, v112, v112
	v_mul_f32_e32 v221, v113, v113
	v_mul_f32_e32 v222, v114, v114
	v_mul_f32_e32 v223, v115, v115
	v_fma_f32 v216, v124, v124, v216
	v_fma_f32 v217, v125, v125, v217
	v_fma_f32 v218, v126, v126, v218
	v_fma_f32 v219, v127, v127, v219
	v_fma_f32 v220, v108, v108, v220
	v_fma_f32 v221, v109, v109, v221
	v_fma_f32 v222, v110, v110, v222
	v_fma_f32 v223, v111, v111, v223
	v_fma_f32 v216, v120, v120, v216
	v_fma_f32 v217, v121, v121, v217
	v_fma_f32 v218, v122, v122, v218
	v_fma_f32 v219, v123, v123, v219
	v_fma_f32 v220, v104, v104, v220
	v_fma_f32 v221, v105, v105, v221
	v_fma_f32 v222, v106, v106, v222
	v_fma_f32 v223, v107, v107, v223
	v_fma_f32 v216, v116, v116, v216
	v_fma_f32 v217, v117, v117, v217
	v_fma_f32 v218, v118, v118, v218
	v_fma_f32 v219, v119, v119, v219
	v_fma_f32 v220, v100, v100, v220
	v_fma_f32 v221, v101, v101, v221
	v_fma_f32 v222, v102, v102, v222
	v_fma_f32 v223, v103, v103, v223
	v_add_f32_e32 v216, v216, v218
	v_add_f32_e32 v217, v217, v219
	v_add_f32_e32 v220, v220, v222
	v_add_f32_e32 v221, v221, v223
	v_add_f32_e32 v208, v216, v217
	v_add_f32_e32 v209, v220, v221
	v_mul_f32_e32 v216, v96, v96
	v_mul_f32_e32 v217, v97, v97
	v_mul_f32_e32 v218, v98, v98
	v_mul_f32_e32 v219, v99, v99
	v_mul_f32_e32 v220, v80, v80
	v_mul_f32_e32 v221, v81, v81
	v_mul_f32_e32 v222, v82, v82
	v_mul_f32_e32 v223, v83, v83
	v_fma_f32 v216, v92, v92, v216
	v_fma_f32 v217, v93, v93, v217
	v_fma_f32 v218, v94, v94, v218
	v_fma_f32 v219, v95, v95, v219
	v_fma_f32 v220, v76, v76, v220
	v_fma_f32 v221, v77, v77, v221
	v_fma_f32 v222, v78, v78, v222
	v_fma_f32 v223, v79, v79, v223
	v_fma_f32 v216, v88, v88, v216
	v_fma_f32 v217, v89, v89, v217
	v_fma_f32 v218, v90, v90, v218
	v_fma_f32 v219, v91, v91, v219
	v_fma_f32 v220, v72, v72, v220
	v_fma_f32 v221, v73, v73, v221
	v_fma_f32 v222, v74, v74, v222
	v_fma_f32 v223, v75, v75, v223
	v_fma_f32 v216, v84, v84, v216
	v_fma_f32 v217, v85, v85, v217
	v_fma_f32 v218, v86, v86, v218
	v_fma_f32 v219, v87, v87, v219
	v_fma_f32 v220, v68, v68, v220
	v_fma_f32 v221, v69, v69, v221
	v_fma_f32 v222, v70, v70, v222
	v_fma_f32 v223, v71, v71, v223
	v_add_f32_e32 v216, v216, v218
	v_add_f32_e32 v217, v217, v219
	v_add_f32_e32 v220, v220, v222
	v_add_f32_e32 v221, v221, v223
	v_add_f32_e32 v210, v216, v217
	v_add_f32_e32 v211, v220, v221
	v_mul_f32_e32 v216, v64, v64
	v_mul_f32_e32 v217, v65, v65
	v_mul_f32_e32 v218, v66, v66
	v_mul_f32_e32 v219, v67, v67
	v_mul_f32_e32 v220, v48, v48
	v_mul_f32_e32 v221, v49, v49
	v_mul_f32_e32 v222, v50, v50
	v_mul_f32_e32 v223, v51, v51
	v_fma_f32 v216, v60, v60, v216
	v_fma_f32 v217, v61, v61, v217
	v_fma_f32 v218, v62, v62, v218
	v_fma_f32 v219, v63, v63, v219
	v_fma_f32 v220, v44, v44, v220
	v_fma_f32 v221, v45, v45, v221
	v_fma_f32 v222, v46, v46, v222
	v_fma_f32 v223, v47, v47, v223
	v_fma_f32 v216, v56, v56, v216
	v_fma_f32 v217, v57, v57, v217
	v_fma_f32 v218, v58, v58, v218
	v_fma_f32 v219, v59, v59, v219
	v_fma_f32 v220, v40, v40, v220
	v_fma_f32 v221, v41, v41, v221
	v_fma_f32 v222, v42, v42, v222
	v_fma_f32 v223, v43, v43, v223
	v_fma_f32 v216, v52, v52, v216
	v_fma_f32 v217, v53, v53, v217
	v_fma_f32 v218, v54, v54, v218
	v_fma_f32 v219, v55, v55, v219
	v_fma_f32 v220, v36, v36, v220
	v_fma_f32 v221, v37, v37, v221
	v_fma_f32 v222, v38, v38, v222
	v_fma_f32 v223, v39, v39, v223
	v_add_f32_e32 v216, v216, v218
	v_add_f32_e32 v217, v217, v219
	v_add_f32_e32 v220, v220, v222
	v_add_f32_e32 v221, v221, v223
	v_add_f32_e32 v212, v216, v217
	v_add_f32_e32 v213, v220, v221
	v_mul_f32_e32 v216, v32, v32
	v_mul_f32_e32 v217, v33, v33
	v_mul_f32_e32 v218, v34, v34
	v_mul_f32_e32 v219, v35, v35
	v_mul_f32_e32 v220, v16, v16
	v_mul_f32_e32 v221, v17, v17
	v_mul_f32_e32 v222, v18, v18
	v_mul_f32_e32 v223, v19, v19
	v_fma_f32 v216, v28, v28, v216
	v_fma_f32 v217, v29, v29, v217
	v_fma_f32 v218, v30, v30, v218
	v_fma_f32 v219, v31, v31, v219
	v_fma_f32 v220, v12, v12, v220
	v_fma_f32 v221, v13, v13, v221
	v_fma_f32 v222, v14, v14, v222
	v_fma_f32 v223, v15, v15, v223
	v_fma_f32 v216, v24, v24, v216
	v_fma_f32 v217, v25, v25, v217
	v_fma_f32 v218, v26, v26, v218
	v_fma_f32 v219, v27, v27, v219
	v_fma_f32 v220, v8, v8, v220
	v_fma_f32 v221, v9, v9, v221
	v_fma_f32 v222, v10, v10, v222
	v_fma_f32 v223, v11, v11, v223
	v_fma_f32 v216, v20, v20, v216
	v_fma_f32 v217, v21, v21, v217
	v_fma_f32 v218, v22, v22, v218
	v_fma_f32 v219, v23, v23, v219
	v_fma_f32 v220, v4, v4, v220
	v_fma_f32 v221, v5, v5, v221
	v_fma_f32 v222, v6, v6, v222
	v_fma_f32 v223, v7, v7, v223
	v_add_f32_e32 v216, v216, v218
	v_add_f32_e32 v217, v217, v219
	v_add_f32_e32 v220, v220, v222
	v_add_f32_e32 v221, v221, v223
	v_add_f32_e32 v214, v216, v217
	v_add_f32_e32 v215, v220, v221
	s_nop 1
	v_permlane32_swap_b32_e32 v208, v209
	v_permlane32_swap_b32_e32 v210, v211
	v_permlane32_swap_b32_e32 v212, v213
	v_permlane32_swap_b32_e32 v214, v215
	v_add_f32_e32 v208, v208, v209
	v_add_f32_e32 v210, v210, v211
	v_add_f32_e32 v212, v212, v213
	v_add_f32_e32 v214, v214, v215
	s_nop 1
	v_permlane16_swap_b32_e32 v208, v210
	v_permlane16_swap_b32_e32 v212, v214
	v_add_f32_e32 v208, v208, v210
	v_add_f32_e32 v212, v212, v214
	v_mul_f32_e32 v208, v190, v208
	v_mul_f32_e32 v212, v191, v212
	v_mul_f32_e32 v208, v190, v208
	v_mul_f32_e32 v212, v191, v212
	v_fmamk_f32 v208, v208, 0x3c800000, v196
	v_fmamk_f32 v212, v212, 0x3c800000, v196
	v_rsq_f32_e32 v208, v208
	v_rsq_f32_e32 v212, v212
	s_nop 0
	v_mul_f32_e32 v190, v190, v208
	v_mul_f32_e32 v191, v191, v212

; __device__ __forceinline__ unsigned cvtpk(float lo, float hi) { f32x2 v = {lo, hi}; bf16x2_t b = __builtin_convertvector(v, bf16x2_t); return __builtin_bit_cast(unsigned, b); }
;     __device__ __forceinline__ void operator()(const f32x4 (&acc)[2][2][4][2], const Unit& u, int wr, int wc, int fr, int fq) const {
;     ...
;                 bf16_t* rowp = base + (size_t)(row0 + ai * HALF + m * 16) * 1024 + colbase;
;                 {   const f32x4 v0 = acc[ai][0][m][0] * mul * g00, v1 = acc[ai][0][m][1] * mul * g01;
;                     u32x4 w; w.x = cvtpk(v0[0], v0[1]); w.y = cvtpk(v0[2], v0[3]); w.z = cvtpk(v1[0], v1[1]); w.w = cvtpk(v1[2], v1[3]);
;                     *(u32x4*)(rowp) = w; }
;                 {   const f32x4 v0 = acc[ai][1][m][0] * mul * g10, v1 = acc[ai][1][m][1] * mul * g11;
;                     u32x4 w; w.x = cvtpk(v0[0], v0[1]); w.y = cvtpk(v0[2], v0[3]); w.z = cvtpk(v1[0], v1[1]); w.w = cvtpk(v1[2], v1[3]);
;                     *(u32x4*)(rowp + 32) = w; }
.Lqe_col:
	v_mul_f32_e32 v128, v128, v148
	v_mul_f32_e32 v129, v129, v148
	v_mul_f32_e32 v130, v130, v148
	v_mul_f32_e32 v131, v131, v148
	v_mul_f32_e32 v124, v124, v148
	v_mul_f32_e32 v125, v125, v148
	v_mul_f32_e32 v126, v126, v148
	v_mul_f32_e32 v127, v127, v148
	v_mul_f32_e32 v120, v120, v148
	v_mul_f32_e32 v121, v121, v148
	v_mul_f32_e32 v122, v122, v148
	v_mul_f32_e32 v123, v123, v148
	v_mul_f32_e32 v116, v116, v148
	v_mul_f32_e32 v117, v117, v148
	v_mul_f32_e32 v118, v118, v148
	v_mul_f32_e32 v119, v119, v148
	v_mul_f32_e32 v128, v132, v128
	v_mul_f32_e32 v129, v133, v129
	v_mul_f32_e32 v130, v134, v130
	v_mul_f32_e32 v131, v135, v131
	v_mul_f32_e32 v124, v136, v124
	v_mul_f32_e32 v125, v137, v125
	v_mul_f32_e32 v126, v138, v126
	v_mul_f32_e32 v127, v139, v127
	v_mul_f32_e32 v120, v140, v120
	v_mul_f32_e32 v121, v141, v121
	v_mul_f32_e32 v122, v142, v122
	v_mul_f32_e32 v123, v143, v123
	v_mul_f32_e32 v116, v144, v116
	v_mul_f32_e32 v117, v145, v117
	v_mul_f32_e32 v118, v146, v118
	v_mul_f32_e32 v119, v147, v119
	v_cvt_pk_bf16_f32 v128, v128, v129
	v_cvt_pk_bf16_f32 v129, v130, v131
	v_cvt_pk_bf16_f32 v130, v124, v125
	v_cvt_pk_bf16_f32 v131, v126, v127
	global_store_dwordx4 v[166:167], v[128:131], off
	v_cvt_pk_bf16_f32 v120, v120, v121
	v_cvt_pk_bf16_f32 v121, v122, v123
	v_cvt_pk_bf16_f32 v122, v116, v117
	v_cvt_pk_bf16_f32 v123, v118, v119
	global_store_dwordx4 v[166:167], v[120:123], off offset:64
	v_mul_f32_e32 v112, v112, v150
	v_mul_f32_e32 v113, v113, v150
	v_mul_f32_e32 v114, v114, v150
	v_mul_f32_e32 v115, v115, v150
	v_mul_f32_e32 v108, v108, v150
	v_mul_f32_e32 v109, v109, v150
	v_mul_f32_e32 v110, v110, v150
	v_mul_f32_e32 v111, v111, v150
	v_mul_f32_e32 v104, v104, v150
	v_mul_f32_e32 v105, v105, v150
	v_mul_f32_e32 v106, v106, v150
	v_mul_f32_e32 v107, v107, v150
	v_mul_f32_e32 v100, v100, v150
	v_mul_f32_e32 v101, v101, v150
	v_mul_f32_e32 v102, v102, v150
	v_mul_f32_e32 v103, v103, v150
	s_mov_b32 s100, 0x8000
	v_lshl_add_u64 v[192:193], v[166:167], 0, s[100:101]
	v_mul_f32_e32 v112, v132, v112
	v_mul_f32_e32 v113, v133, v113
	v_mul_f32_e32 v114, v134, v114
	v_mul_f32_e32 v115, v135, v115
	v_mul_f32_e32 v108, v136, v108
	v_mul_f32_e32 v109, v137, v109
	v_mul_f32_e32 v110, v138, v110
	v_mul_f32_e32 v111, v139, v111
	v_mul_f32_e32 v104, v140, v104
	v_mul_f32_e32 v105, v141, v105
	v_mul_f32_e32 v106, v142, v106
	v_mul_f32_e32 v107, v143, v107
	v_mul_f32_e32 v100, v144, v100
	v_mul_f32_e32 v101, v145, v101
	v_mul_f32_e32 v102, v146, v102
	v_mul_f32_e32 v103, v147, v103
	v_cvt_pk_bf16_f32 v112, v112, v113
	v_cvt_pk_bf16_f32 v113, v114, v115
	v_cvt_pk_bf16_f32 v114, v108, v109
	v_cvt_pk_bf16_f32 v115, v110, v111
	global_store_dwordx4 v[192:193], v[112:115], off
	v_cvt_pk_bf16_f32 v104, v104, v105
	v_cvt_pk_bf16_f32 v105, v106, v107
	v_cvt_pk_bf16_f32 v106, v100, v101
	v_cvt_pk_bf16_f32 v107, v102, v103
	global_store_dwordx4 v[192:193], v[104:107], off offset:64
	v_mul_f32_e32 v96, v96, v152
	v_mul_f32_e32 v97, v97, v152
	v_mul_f32_e32 v98, v98, v152
	v_mul_f32_e32 v99, v99, v152
	v_mul_f32_e32 v92, v92, v152
	v_mul_f32_e32 v93, v93, v152
	v_mul_f32_e32 v94, v94, v152
	v_mul_f32_e32 v95, v95, v152
	v_mul_f32_e32 v88, v88, v152
	v_mul_f32_e32 v89, v89, v152
	v_mul_f32_e32 v90, v90, v152
	v_mul_f32_e32 v91, v91, v152
	v_mul_f32_e32 v84, v84, v152
	v_mul_f32_e32 v85, v85, v152
	v_mul_f32_e32 v86, v86, v152
	v_mul_f32_e32 v87, v87, v152
	s_mov_b32 s100, 0x10000
	v_lshl_add_u64 v[192:193], v[166:167], 0, s[100:101]
	v_mul_f32_e32 v96, v132, v96
	v_mul_f32_e32 v97, v133, v97
	v_mul_f32_e32 v98, v134, v98
	v_mul_f32_e32 v99, v135, v99
	v_mul_f32_e32 v92, v136, v92
	v_mul_f32_e32 v93, v137, v93
	v_mul_f32_e32 v94, v138, v94
	v_mul_f32_e32 v95, v139, v95
	v_mul_f32_e32 v88, v140, v88
	v_mul_f32_e32 v89, v141, v89
	v_mul_f32_e32 v90, v142, v90
	v_mul_f32_e32 v91, v143, v91
	v_mul_f32_e32 v84, v144, v84
	v_mul_f32_e32 v85, v145, v85
	v_mul_f32_e32 v86, v146, v86
	v_mul_f32_e32 v87, v147, v87
	v_cvt_pk_bf16_f32 v96, v96, v97
	v_cvt_pk_bf16_f32 v97, v98, v99
	v_cvt_pk_bf16_f32 v98, v92, v93
	v_cvt_pk_bf16_f32 v99, v94, v95
	global_store_dwordx4 v[192:193], v[96:99], off
	v_cvt_pk_bf16_f32 v88, v88, v89
	v_cvt_pk_bf16_f32 v89, v90, v91
	v_cvt_pk_bf16_f32 v90, v84, v85
	v_cvt_pk_bf16_f32 v91, v86, v87
	global_store_dwordx4 v[192:193], v[88:91], off offset:64
	v_mul_f32_e32 v80, v80, v154
	v_mul_f32_e32 v81, v81, v154
	v_mul_f32_e32 v82, v82, v154
	v_mul_f32_e32 v83, v83, v154
	v_mul_f32_e32 v76, v76, v154
	v_mul_f32_e32 v77, v77, v154
	v_mul_f32_e32 v78, v78, v154
	v_mul_f32_e32 v79, v79, v154
	v_mul_f32_e32 v72, v72, v154
	v_mul_f32_e32 v73, v73, v154
	v_mul_f32_e32 v74, v74, v154
	v_mul_f32_e32 v75, v75, v154
	v_mul_f32_e32 v68, v68, v154
	v_mul_f32_e32 v69, v69, v154
	v_mul_f32_e32 v70, v70, v154
	v_mul_f32_e32 v71, v71, v154
	s_mov_b32 s100, 0x18000
	v_lshl_add_u64 v[192:193], v[166:167], 0, s[100:101]
	v_mul_f32_e32 v80, v132, v80
	v_mul_f32_e32 v81, v133, v81
	v_mul_f32_e32 v82, v134, v82
	v_mul_f32_e32 v83, v135, v83
	v_mul_f32_e32 v76, v136, v76
	v_mul_f32_e32 v77, v137, v77
	v_mul_f32_e32 v78, v138, v78
	v_mul_f32_e32 v79, v139, v79
	v_mul_f32_e32 v72, v140, v72
	v_mul_f32_e32 v73, v141, v73
	v_mul_f32_e32 v74, v142, v74
	v_mul_f32_e32 v75, v143, v75
	v_mul_f32_e32 v68, v144, v68
	v_mul_f32_e32 v69, v145, v69
	v_mul_f32_e32 v70, v146, v70
	v_mul_f32_e32 v71, v147, v71
	v_cvt_pk_bf16_f32 v80, v80, v81
	v_cvt_pk_bf16_f32 v81, v82, v83
	v_cvt_pk_bf16_f32 v82, v76, v77
	v_cvt_pk_bf16_f32 v83, v78, v79
	global_store_dwordx4 v[192:193], v[80:83], off
	v_cvt_pk_bf16_f32 v72, v72, v73
	v_cvt_pk_bf16_f32 v73, v74, v75
; __device__ __forceinline__ unsigned cvtpk(float lo, float hi) { f32x2 v = {lo, hi}; bf16x2_t b = __builtin_convertvector(v, bf16x2_t); return __builtin_bit_cast(unsigned, b); }
;     __device__ __forceinline__ void operator()(const f32x4 (&acc)[2][2][4][2], const Unit& u, int wr, int wc, int fr, int fq) const {
;     ...
;                 bf16_t* rowp = base + (size_t)(row0 + ai * HALF + m * 16) * 1024 + colbase;
;                 {   const f32x4 v0 = acc[ai][0][m][0] * mul * g00, v1 = acc[ai][0][m][1] * mul * g01;
;                     u32x4 w; w.x = cvtpk(v0[0], v0[1]); w.y = cvtpk(v0[2], v0[3]); w.z = cvtpk(v1[0], v1[1]); w.w = cvtpk(v1[2], v1[3]);
;                     *(u32x4*)(rowp) = w; }
;                 {   const f32x4 v0 = acc[ai][1][m][0] * mul * g10, v1 = acc[ai][1][m][1] * mul * g11;
;                     u32x4 w; w.x = cvtpk(v0[0], v0[1]); w.y = cvtpk(v0[2], v0[3]); w.z = cvtpk(v1[0], v1[1]); w.w = cvtpk(v1[2], v1[3]);
;                     *(u32x4*)(rowp + 32) = w; }
	v_cvt_pk_bf16_f32 v74, v68, v69
	v_cvt_pk_bf16_f32 v75, v70, v71
	global_store_dwordx4 v[192:193], v[72:75], off offset:64
	v_mul_f32_e32 v64, v64, v156
	v_mul_f32_e32 v65, v65, v156
	v_mul_f32_e32 v66, v66, v156
	v_mul_f32_e32 v67, v67, v156
	v_mul_f32_e32 v60, v60, v156
	v_mul_f32_e32 v61, v61, v156
	v_mul_f32_e32 v62, v62, v156
	v_mul_f32_e32 v63, v63, v156
	v_mul_f32_e32 v56, v56, v156
	v_mul_f32_e32 v57, v57, v156
	v_mul_f32_e32 v58, v58, v156
	v_mul_f32_e32 v59, v59, v156
	v_mul_f32_e32 v52, v52, v156
	v_mul_f32_e32 v53, v53, v156
	v_mul_f32_e32 v54, v54, v156
	v_mul_f32_e32 v55, v55, v156
	s_mov_b32 s100, 0x40000
	v_lshl_add_u64 v[192:193], v[166:167], 0, s[100:101]
	v_mul_f32_e32 v64, v132, v64
	v_mul_f32_e32 v65, v133, v65
	v_mul_f32_e32 v66, v134, v66
	v_mul_f32_e32 v67, v135, v67
	v_mul_f32_e32 v60, v136, v60
	v_mul_f32_e32 v61, v137, v61
	v_mul_f32_e32 v62, v138, v62
	v_mul_f32_e32 v63, v139, v63
	v_mul_f32_e32 v56, v140, v56
	v_mul_f32_e32 v57, v141, v57
	v_mul_f32_e32 v58, v142, v58
	v_mul_f32_e32 v59, v143, v59
	v_mul_f32_e32 v52, v144, v52
	v_mul_f32_e32 v53, v145, v53
	v_mul_f32_e32 v54, v146, v54
	v_mul_f32_e32 v55, v147, v55
	v_cvt_pk_bf16_f32 v64, v64, v65
	v_cvt_pk_bf16_f32 v65, v66, v67
	v_cvt_pk_bf16_f32 v66, v60, v61
	v_cvt_pk_bf16_f32 v67, v62, v63
	global_store_dwordx4 v[192:193], v[64:67], off
	v_cvt_pk_bf16_f32 v56, v56, v57
	v_cvt_pk_bf16_f32 v57, v58, v59
	v_cvt_pk_bf16_f32 v58, v52, v53
	v_cvt_pk_bf16_f32 v59, v54, v55
	global_store_dwordx4 v[192:193], v[56:59], off offset:64
	v_mul_f32_e32 v48, v48, v158
	v_mul_f32_e32 v49, v49, v158
	v_mul_f32_e32 v50, v50, v158
	v_mul_f32_e32 v51, v51, v158
	v_mul_f32_e32 v44, v44, v158
	v_mul_f32_e32 v45, v45, v158
	v_mul_f32_e32 v46, v46, v158
	v_mul_f32_e32 v47, v47, v158
	v_mul_f32_e32 v40, v40, v158
	v_mul_f32_e32 v41, v41, v158
	v_mul_f32_e32 v42, v42, v158
	v_mul_f32_e32 v43, v43, v158
	v_mul_f32_e32 v36, v36, v158
	v_mul_f32_e32 v37, v37, v158
	v_mul_f32_e32 v38, v38, v158
	v_mul_f32_e32 v39, v39, v158
	s_mov_b32 s100, 0x48000
	v_lshl_add_u64 v[192:193], v[166:167], 0, s[100:101]
	v_mul_f32_e32 v48, v132, v48
	v_mul_f32_e32 v49, v133, v49
	v_mul_f32_e32 v50, v134, v50
	v_mul_f32_e32 v51, v135, v51
	v_mul_f32_e32 v44, v136, v44
	v_mul_f32_e32 v45, v137, v45
	v_mul_f32_e32 v46, v138, v46
	v_mul_f32_e32 v47, v139, v47
	v_mul_f32_e32 v40, v140, v40
	v_mul_f32_e32 v41, v141, v41
	v_mul_f32_e32 v42, v142, v42
	v_mul_f32_e32 v43, v143, v43
	v_mul_f32_e32 v36, v144, v36
	v_mul_f32_e32 v37, v145, v37
	v_mul_f32_e32 v38, v146, v38
	v_mul_f32_e32 v39, v147, v39
	v_cvt_pk_bf16_f32 v48, v48, v49
	v_cvt_pk_bf16_f32 v49, v50, v51
	v_cvt_pk_bf16_f32 v50, v44, v45
	v_cvt_pk_bf16_f32 v51, v46, v47
	global_store_dwordx4 v[192:193], v[48:51], off
	v_cvt_pk_bf16_f32 v40, v40, v41
	v_cvt_pk_bf16_f32 v41, v42, v43
	v_cvt_pk_bf16_f32 v42, v36, v37
	v_cvt_pk_bf16_f32 v43, v38, v39
	global_store_dwordx4 v[192:193], v[40:43], off offset:64
	v_mul_f32_e32 v32, v32, v160
	v_mul_f32_e32 v33, v33, v160
	v_mul_f32_e32 v34, v34, v160
	v_mul_f32_e32 v35, v35, v160
	v_mul_f32_e32 v28, v28, v160
	v_mul_f32_e32 v29, v29, v160
	v_mul_f32_e32 v30, v30, v160
	v_mul_f32_e32 v31, v31, v160
	v_mul_f32_e32 v24, v24, v160
	v_mul_f32_e32 v25, v25, v160
	v_mul_f32_e32 v26, v26, v160
	v_mul_f32_e32 v27, v27, v160
	v_mul_f32_e32 v20, v20, v160
	v_mul_f32_e32 v21, v21, v160
	v_mul_f32_e32 v22, v22, v160
	v_mul_f32_e32 v23, v23, v160
	s_mov_b32 s100, 0x50000
	v_lshl_add_u64 v[192:193], v[166:167], 0, s[100:101]
	v_mul_f32_e32 v32, v132, v32
	v_mul_f32_e32 v33, v133, v33
	v_mul_f32_e32 v34, v134, v34
	v_mul_f32_e32 v35, v135, v35
	v_mul_f32_e32 v28, v136, v28
	v_mul_f32_e32 v29, v137, v29
	v_mul_f32_e32 v30, v138, v30
	v_mul_f32_e32 v31, v139, v31
	v_mul_f32_e32 v24, v140, v24
	v_mul_f32_e32 v25, v141, v25
	v_mul_f32_e32 v26, v142, v26
	v_mul_f32_e32 v27, v143, v27
	v_mul_f32_e32 v20, v144, v20
	v_mul_f32_e32 v21, v145, v21
	v_mul_f32_e32 v22, v146, v22
	v_mul_f32_e32 v23, v147, v23
	v_cvt_pk_bf16_f32 v32, v32, v33
	v_cvt_pk_bf16_f32 v33, v34, v35
	v_cvt_pk_bf16_f32 v34, v28, v29
	v_cvt_pk_bf16_f32 v35, v30, v31
	global_store_dwordx4 v[192:193], v[32:35], off
	v_cvt_pk_bf16_f32 v24, v24, v25
	v_cvt_pk_bf16_f32 v25, v26, v27
	v_cvt_pk_bf16_f32 v26, v20, v21
	v_cvt_pk_bf16_f32 v27, v22, v23
	global_store_dwordx4 v[192:193], v[24:27], off offset:64
	v_mul_f32_e32 v16, v16, v162
	v_mul_f32_e32 v17, v17, v162
	v_mul_f32_e32 v18, v18, v162
	v_mul_f32_e32 v19, v19, v162
	v_mul_f32_e32 v12, v12, v162
	v_mul_f32_e32 v13, v13, v162
	v_mul_f32_e32 v14, v14, v162
	v_mul_f32_e32 v15, v15, v162
	v_mul_f32_e32 v8, v8, v162
	v_mul_f32_e32 v9, v9, v162
	v_mul_f32_e32 v10, v10, v162
	v_mul_f32_e32 v11, v11, v162
	v_mul_f32_e32 v4, v4, v162
	v_mul_f32_e32 v5, v5, v162
	v_mul_f32_e32 v6, v6, v162
	v_mul_f32_e32 v7, v7, v162
	s_mov_b32 s100, 0x58000
	v_lshl_add_u64 v[192:193], v[166:167], 0, s[100:101]
	v_mul_f32_e32 v16, v132, v16
	v_mul_f32_e32 v17, v133, v17
	v_mul_f32_e32 v18, v134, v18
	v_mul_f32_e32 v19, v135, v19
	v_mul_f32_e32 v12, v136, v12
	v_mul_f32_e32 v13, v137, v13
	v_mul_f32_e32 v14, v138, v14
	v_mul_f32_e32 v15, v139, v15
	v_mul_f32_e32 v8, v140, v8
	v_mul_f32_e32 v9, v141, v9
	v_mul_f32_e32 v10, v142, v10
	v_mul_f32_e32 v11, v143, v11
	v_mul_f32_e32 v4, v144, v4
	v_mul_f32_e32 v5, v145, v5
	v_mul_f32_e32 v6, v146, v6
	v_mul_f32_e32 v7, v147, v7
	v_cvt_pk_bf16_f32 v16, v16, v17
	v_cvt_pk_bf16_f32 v17, v18, v19
	v_cvt_pk_bf16_f32 v18, v12, v13
	v_cvt_pk_bf16_f32 v19, v14, v15
	global_store_dwordx4 v[192:193], v[16:19], off
	v_cvt_pk_bf16_f32 v8, v8, v9
	v_cvt_pk_bf16_f32 v9, v10, v11
	v_cvt_pk_bf16_f32 v10, v4, v5
	v_cvt_pk_bf16_f32 v11, v6, v7
	global_store_dwordx4 v[192:193], v[8:11], off offset:64
	s_branch .Lqe_tail
; __device__ __forceinline__ unsigned cvtpk(float lo, float hi) { f32x2 v = {lo, hi}; bf16x2_t b = __builtin_convertvector(v, bf16x2_t); return __builtin_bit_cast(unsigned, b); }
;     __device__ __forceinline__ void operator()(const f32x4 (&acc)[2][2][4][2], const Unit& u, int wr, int wc, int fr, int fq) const {
;     ...
;                 bf16_t* rowp = base + (size_t)(row0 + ai * HALF + m * 16) * 1024 + colbase;
;                 {   const f32x4 v0 = acc[ai][0][m][0] * mul * g00, v1 = acc[ai][0][m][1] * mul * g01;
;                     u32x4 w; w.x = cvtpk(v0[0], v0[1]); w.y = cvtpk(v0[2], v0[3]); w.z = cvtpk(v1[0], v1[1]); w.w = cvtpk(v1[2], v1[3]);
;                     *(u32x4*)(rowp) = w; }
;                 {   const f32x4 v0 = acc[ai][1][m][0] * mul * g10, v1 = acc[ai][1][m][1] * mul * g11;
;                     u32x4 w; w.x = cvtpk(v0[0], v0[1]); w.y = cvtpk(v0[2], v0[3]); w.z = cvtpk(v1[0], v1[1]); w.w = cvtpk(v1[2], v1[3]);
;                     *(u32x4*)(rowp + 32) = w; }
.Lqe_plain:
	v_mul_f32_e32 v128, v128, v148
	v_mul_f32_e32 v129, v129, v148
	v_mul_f32_e32 v130, v130, v148
	v_mul_f32_e32 v131, v131, v148
	v_mul_f32_e32 v124, v124, v148
	v_mul_f32_e32 v125, v125, v148
	v_mul_f32_e32 v126, v126, v148
	v_mul_f32_e32 v127, v127, v148
	v_mul_f32_e32 v120, v120, v148
	v_mul_f32_e32 v121, v121, v148
	v_mul_f32_e32 v122, v122, v148
	v_mul_f32_e32 v123, v123, v148
	v_mul_f32_e32 v116, v116, v148
	v_mul_f32_e32 v117, v117, v148
	v_mul_f32_e32 v118, v118, v148
	v_mul_f32_e32 v119, v119, v148
	v_cvt_pk_bf16_f32 v128, v128, v129
	v_cvt_pk_bf16_f32 v129, v130, v131
	v_cvt_pk_bf16_f32 v130, v124, v125
	v_cvt_pk_bf16_f32 v131, v126, v127
	global_store_dwordx4 v[166:167], v[128:131], off
	v_cvt_pk_bf16_f32 v120, v120, v121
	v_cvt_pk_bf16_f32 v121, v122, v123
	v_cvt_pk_bf16_f32 v122, v116, v117
	v_cvt_pk_bf16_f32 v123, v118, v119
	global_store_dwordx4 v[166:167], v[120:123], off offset:64
	v_mul_f32_e32 v112, v112, v150
	v_mul_f32_e32 v113, v113, v150
	v_mul_f32_e32 v114, v114, v150
	v_mul_f32_e32 v115, v115, v150
	v_mul_f32_e32 v108, v108, v150
	v_mul_f32_e32 v109, v109, v150
	v_mul_f32_e32 v110, v110, v150
	v_mul_f32_e32 v111, v111, v150
	v_mul_f32_e32 v104, v104, v150
	v_mul_f32_e32 v105, v105, v150
	v_mul_f32_e32 v106, v106, v150
	v_mul_f32_e32 v107, v107, v150
	v_mul_f32_e32 v100, v100, v150
	v_mul_f32_e32 v101, v101, v150
	v_mul_f32_e32 v102, v102, v150
	v_mul_f32_e32 v103, v103, v150
	s_mov_b32 s100, 0x8000
	v_lshl_add_u64 v[192:193], v[166:167], 0, s[100:101]
	v_cvt_pk_bf16_f32 v112, v112, v113
	v_cvt_pk_bf16_f32 v113, v114, v115
	v_cvt_pk_bf16_f32 v114, v108, v109
	v_cvt_pk_bf16_f32 v115, v110, v111
	global_store_dwordx4 v[192:193], v[112:115], off
	v_cvt_pk_bf16_f32 v104, v104, v105
	v_cvt_pk_bf16_f32 v105, v106, v107
	v_cvt_pk_bf16_f32 v106, v100, v101
	v_cvt_pk_bf16_f32 v107, v102, v103
	global_store_dwordx4 v[192:193], v[104:107], off offset:64
	v_mul_f32_e32 v96, v96, v152
	v_mul_f32_e32 v97, v97, v152
	v_mul_f32_e32 v98, v98, v152
	v_mul_f32_e32 v99, v99, v152
	v_mul_f32_e32 v92, v92, v152
	v_mul_f32_e32 v93, v93, v152
	v_mul_f32_e32 v94, v94, v152
	v_mul_f32_e32 v95, v95, v152
	v_mul_f32_e32 v88, v88, v152
	v_mul_f32_e32 v89, v89, v152
	v_mul_f32_e32 v90, v90, v152
	v_mul_f32_e32 v91, v91, v152
	v_mul_f32_e32 v84, v84, v152
	v_mul_f32_e32 v85, v85, v152
	v_mul_f32_e32 v86, v86, v152
	v_mul_f32_e32 v87, v87, v152
	s_mov_b32 s100, 0x10000
	v_lshl_add_u64 v[192:193], v[166:167], 0, s[100:101]
	v_cvt_pk_bf16_f32 v96, v96, v97
	v_cvt_pk_bf16_f32 v97, v98, v99
	v_cvt_pk_bf16_f32 v98, v92, v93
	v_cvt_pk_bf16_f32 v99, v94, v95
	global_store_dwordx4 v[192:193], v[96:99], off
	v_cvt_pk_bf16_f32 v88, v88, v89
	v_cvt_pk_bf16_f32 v89, v90, v91
	v_cvt_pk_bf16_f32 v90, v84, v85
	v_cvt_pk_bf16_f32 v91, v86, v87
	global_store_dwordx4 v[192:193], v[88:91], off offset:64
	v_mul_f32_e32 v80, v80, v154
	v_mul_f32_e32 v81, v81, v154
	v_mul_f32_e32 v82, v82, v154
	v_mul_f32_e32 v83, v83, v154
	v_mul_f32_e32 v76, v76, v154
	v_mul_f32_e32 v77, v77, v154
	v_mul_f32_e32 v78, v78, v154
	v_mul_f32_e32 v79, v79, v154
	v_mul_f32_e32 v72, v72, v154
	v_mul_f32_e32 v73, v73, v154
	v_mul_f32_e32 v74, v74, v154
	v_mul_f32_e32 v75, v75, v154
	v_mul_f32_e32 v68, v68, v154
	v_mul_f32_e32 v69, v69, v154
	v_mul_f32_e32 v70, v70, v154
	v_mul_f32_e32 v71, v71, v154
	s_mov_b32 s100, 0x18000
	v_lshl_add_u64 v[192:193], v[166:167], 0, s[100:101]
	v_cvt_pk_bf16_f32 v80, v80, v81
	v_cvt_pk_bf16_f32 v81, v82, v83
	v_cvt_pk_bf16_f32 v82, v76, v77
	v_cvt_pk_bf16_f32 v83, v78, v79
	global_store_dwordx4 v[192:193], v[80:83], off
	v_cvt_pk_bf16_f32 v72, v72, v73
	v_cvt_pk_bf16_f32 v73, v74, v75
	v_cvt_pk_bf16_f32 v74, v68, v69
	v_cvt_pk_bf16_f32 v75, v70, v71
; __device__ __forceinline__ unsigned cvtpk(float lo, float hi) { f32x2 v = {lo, hi}; bf16x2_t b = __builtin_convertvector(v, bf16x2_t); return __builtin_bit_cast(unsigned, b); }
;     __device__ __forceinline__ void operator()(const f32x4 (&acc)[2][2][4][2], const Unit& u, int wr, int wc, int fr, int fq) const {
;     ...
;                 bf16_t* rowp = base + (size_t)(row0 + ai * HALF + m * 16) * 1024 + colbase;
;                 {   const f32x4 v0 = acc[ai][0][m][0] * mul * g00, v1 = acc[ai][0][m][1] * mul * g01;
;                     u32x4 w; w.x = cvtpk(v0[0], v0[1]); w.y = cvtpk(v0[2], v0[3]); w.z = cvtpk(v1[0], v1[1]); w.w = cvtpk(v1[2], v1[3]);
;                     *(u32x4*)(rowp) = w; }
;                 {   const f32x4 v0 = acc[ai][1][m][0] * mul * g10, v1 = acc[ai][1][m][1] * mul * g11;
;                     u32x4 w; w.x = cvtpk(v0[0], v0[1]); w.y = cvtpk(v0[2], v0[3]); w.z = cvtpk(v1[0], v1[1]); w.w = cvtpk(v1[2], v1[3]);
;                     *(u32x4*)(rowp + 32) = w; }
	global_store_dwordx4 v[192:193], v[72:75], off offset:64
	v_mul_f32_e32 v64, v64, v156
	v_mul_f32_e32 v65, v65, v156
	v_mul_f32_e32 v66, v66, v156
	v_mul_f32_e32 v67, v67, v156
	v_mul_f32_e32 v60, v60, v156
	v_mul_f32_e32 v61, v61, v156
	v_mul_f32_e32 v62, v62, v156
	v_mul_f32_e32 v63, v63, v156
	v_mul_f32_e32 v56, v56, v156
	v_mul_f32_e32 v57, v57, v156
	v_mul_f32_e32 v58, v58, v156
	v_mul_f32_e32 v59, v59, v156
	v_mul_f32_e32 v52, v52, v156
	v_mul_f32_e32 v53, v53, v156
	v_mul_f32_e32 v54, v54, v156
	v_mul_f32_e32 v55, v55, v156
	s_mov_b32 s100, 0x40000
	v_lshl_add_u64 v[192:193], v[166:167], 0, s[100:101]
	v_cvt_pk_bf16_f32 v64, v64, v65
	v_cvt_pk_bf16_f32 v65, v66, v67
	v_cvt_pk_bf16_f32 v66, v60, v61
	v_cvt_pk_bf16_f32 v67, v62, v63
	global_store_dwordx4 v[192:193], v[64:67], off
	v_cvt_pk_bf16_f32 v56, v56, v57
	v_cvt_pk_bf16_f32 v57, v58, v59
	v_cvt_pk_bf16_f32 v58, v52, v53
	v_cvt_pk_bf16_f32 v59, v54, v55
	global_store_dwordx4 v[192:193], v[56:59], off offset:64
	v_mul_f32_e32 v48, v48, v158
	v_mul_f32_e32 v49, v49, v158
	v_mul_f32_e32 v50, v50, v158
	v_mul_f32_e32 v51, v51, v158
	v_mul_f32_e32 v44, v44, v158
	v_mul_f32_e32 v45, v45, v158
	v_mul_f32_e32 v46, v46, v158
	v_mul_f32_e32 v47, v47, v158
	v_mul_f32_e32 v40, v40, v158
	v_mul_f32_e32 v41, v41, v158
	v_mul_f32_e32 v42, v42, v158
	v_mul_f32_e32 v43, v43, v158
	v_mul_f32_e32 v36, v36, v158
	v_mul_f32_e32 v37, v37, v158
	v_mul_f32_e32 v38, v38, v158
	v_mul_f32_e32 v39, v39, v158
	s_mov_b32 s100, 0x48000
	v_lshl_add_u64 v[192:193], v[166:167], 0, s[100:101]
	v_cvt_pk_bf16_f32 v48, v48, v49
	v_cvt_pk_bf16_f32 v49, v50, v51
	v_cvt_pk_bf16_f32 v50, v44, v45
	v_cvt_pk_bf16_f32 v51, v46, v47
	global_store_dwordx4 v[192:193], v[48:51], off
	v_cvt_pk_bf16_f32 v40, v40, v41
	v_cvt_pk_bf16_f32 v41, v42, v43
	v_cvt_pk_bf16_f32 v42, v36, v37
	v_cvt_pk_bf16_f32 v43, v38, v39
	global_store_dwordx4 v[192:193], v[40:43], off offset:64
	v_mul_f32_e32 v32, v32, v160
	v_mul_f32_e32 v33, v33, v160
	v_mul_f32_e32 v34, v34, v160
	v_mul_f32_e32 v35, v35, v160
	v_mul_f32_e32 v28, v28, v160
	v_mul_f32_e32 v29, v29, v160
	v_mul_f32_e32 v30, v30, v160
	v_mul_f32_e32 v31, v31, v160
	v_mul_f32_e32 v24, v24, v160
	v_mul_f32_e32 v25, v25, v160
	v_mul_f32_e32 v26, v26, v160
	v_mul_f32_e32 v27, v27, v160
	v_mul_f32_e32 v20, v20, v160
	v_mul_f32_e32 v21, v21, v160
	v_mul_f32_e32 v22, v22, v160
	v_mul_f32_e32 v23, v23, v160
	s_mov_b32 s100, 0x50000
	v_lshl_add_u64 v[192:193], v[166:167], 0, s[100:101]
	v_cvt_pk_bf16_f32 v32, v32, v33
	v_cvt_pk_bf16_f32 v33, v34, v35
	v_cvt_pk_bf16_f32 v34, v28, v29
	v_cvt_pk_bf16_f32 v35, v30, v31
	global_store_dwordx4 v[192:193], v[32:35], off
	v_cvt_pk_bf16_f32 v24, v24, v25
	v_cvt_pk_bf16_f32 v25, v26, v27
	v_cvt_pk_bf16_f32 v26, v20, v21
	v_cvt_pk_bf16_f32 v27, v22, v23
	global_store_dwordx4 v[192:193], v[24:27], off offset:64
	v_mul_f32_e32 v16, v16, v162
	v_mul_f32_e32 v17, v17, v162
	v_mul_f32_e32 v18, v18, v162
	v_mul_f32_e32 v19, v19, v162
	v_mul_f32_e32 v12, v12, v162
	v_mul_f32_e32 v13, v13, v162
	v_mul_f32_e32 v14, v14, v162
	v_mul_f32_e32 v15, v15, v162
	v_mul_f32_e32 v8, v8, v162
	v_mul_f32_e32 v9, v9, v162
	v_mul_f32_e32 v10, v10, v162
	v_mul_f32_e32 v11, v11, v162
	v_mul_f32_e32 v4, v4, v162
	v_mul_f32_e32 v5, v5, v162
	v_mul_f32_e32 v6, v6, v162
	v_mul_f32_e32 v7, v7, v162
	s_mov_b32 s100, 0x58000
	v_lshl_add_u64 v[192:193], v[166:167], 0, s[100:101]
	v_cvt_pk_bf16_f32 v16, v16, v17
	v_cvt_pk_bf16_f32 v17, v18, v19
	v_cvt_pk_bf16_f32 v18, v12, v13
	v_cvt_pk_bf16_f32 v19, v14, v15
	global_store_dwordx4 v[192:193], v[16:19], off
	v_cvt_pk_bf16_f32 v8, v8, v9
	v_cvt_pk_bf16_f32 v9, v10, v11
	v_cvt_pk_bf16_f32 v10, v4, v5
	v_cvt_pk_bf16_f32 v11, v6, v7
	global_store_dwordx4 v[192:193], v[8:11], off offset:64

; __device__ __forceinline__ unsigned cvtpk(float lo, float hi) { f32x2 v = {lo, hi}; bf16x2_t b = __builtin_convertvector(v, bf16x2_t); return __builtin_bit_cast(unsigned, b); }
;     __device__ __forceinline__ void operator()(const f32x4 (&acc)[2][2][4][2], const Unit& u, int wr, int wc, int fr, int fq) const {
;     ...
;                 for (int bj = 0; bj < 2; ++bj) w[ai][m][bj] = *(const u32x4*)(xb + (size_t)(row0 + ai * HALF + m * 16) * 1024 + col0 + bj * HALF);
; #pragma unroll
;         for (int ai = 0; ai < 2; ++ai)
; #pragma unroll
;             for (int m = 0; m < 4; ++m) {
;                 const int row = row0 + ai * HALF + m * 16;
;                 const size_t off = (size_t)row * 1024 + col0;
;                 float ss = 0.f;
; #pragma unroll
;                 for (int bj = 0; bj < 2; ++bj) {
;                     const u32x4 wv = w[ai][m][bj];
;                     f32x4 o0 = acc[ai][bj][m][0], o1 = acc[ai][bj][m][1];
;                     o0[0] += __builtin_bit_cast(float, wv.x << 16); o0[1] += __builtin_bit_cast(float, wv.x & 0xffff0000u); o0[2] += __builtin_bit_cast(float, wv.y << 16); o0[3] += __builtin_bit_cast(float, wv.y & 0xffff0000u);
;                     o1[0] += __builtin_bit_cast(float, wv.z << 16); o1[1] += __builtin_bit_cast(float, wv.z & 0xffff0000u); o1[2] += __builtin_bit_cast(float, wv.w << 16); o1[3] += __builtin_bit_cast(float, wv.w & 0xffff0000u);
;                     if (last) { *(f32x4*)(out + off + bj * HALF) = o0; *(f32x4*)(out + off + bj * HALF + 4) = o1; }
;                     else {
;                         u32x4 v; v.x = cvtpk(o0[0], o0[1]); v.y = cvtpk(o0[2], o0[3]); v.z = cvtpk(o1[0], o1[1]); v.w = cvtpk(o1[2], o1[3]);
;                         *(u32x4*)(xb + off + bj * HALF) = v;
;                         ss += (o0[0] * o0[0] + o0[1] * o0[1]) + (o0[2] * o0[2] + o0[3] * o0[3]) + (o1[0] * o1[0] + o1[1] * o1[1]) + (o1[2] * o1[2] + o1[3] * o1[3]);
.LBB0_332:
	v_lshl_add_u32 v212, s26, 8, v3
	v_lshl_or_b32 v213, s24, 8, v252
	v_lshlrev_b32_e32 v230, 1, v213
	v_lshl_add_u32 v230, v212, 11, v230
	v_mov_b32_e32 v231, v2
	s_mov_b32 s101, 0
	s_mov_b32 s28, 0xffff0000
	v_lshl_add_u64 v[214:215], s[10:11], 0, v[230:231]
	global_load_dwordx4 v[192:195], v[214:215], off
	global_load_dwordx4 v[188:191], v[214:215], off offset:256
	s_mov_b32 s100, 0x8000
	v_lshl_add_u64 v[216:217], v[214:215], 0, s[100:101]
	global_load_dwordx4 v[184:187], v[216:217], off
	global_load_dwordx4 v[180:183], v[216:217], off offset:256
	s_mov_b32 s100, 0x10000
	v_lshl_add_u64 v[218:219], v[214:215], 0, s[100:101]
	global_load_dwordx4 v[176:179], v[218:219], off
	global_load_dwordx4 v[172:175], v[218:219], off offset:256
	s_mov_b32 s100, 0x18000
	v_lshl_add_u64 v[220:221], v[214:215], 0, s[100:101]
	global_load_dwordx4 v[168:171], v[220:221], off
	global_load_dwordx4 v[164:167], v[220:221], off offset:256
	s_mov_b32 s100, 0x40000
	v_lshl_add_u64 v[222:223], v[214:215], 0, s[100:101]
	global_load_dwordx4 v[156:159], v[222:223], off
	global_load_dwordx4 v[148:151], v[222:223], off offset:256
	s_mov_b32 s100, 0x48000
	v_lshl_add_u64 v[224:225], v[214:215], 0, s[100:101]
	global_load_dwordx4 v[140:143], v[224:225], off
	global_load_dwordx4 v[132:135], v[224:225], off offset:256
	s_mov_b32 s100, 0x50000
	v_lshl_add_u64 v[226:227], v[214:215], 0, s[100:101]
	global_load_dwordx4 v[128:131], v[226:227], off
	global_load_dwordx4 v[112:115], v[226:227], off offset:256
	s_mov_b32 s100, 0x58000
	v_lshl_add_u64 v[228:229], v[214:215], 0, s[100:101]
	global_load_dwordx4 v[124:127], v[228:229], off
	global_load_dwordx4 v[108:111], v[228:229], off offset:256
	s_waitcnt vmcnt(14)
	v_lshlrev_b32_e32 v230, 16, v192
	v_and_b32_e32 v231, s28, v192
	v_lshlrev_b32_e32 v232, 16, v193
	v_and_b32_e32 v233, s28, v193
	v_lshlrev_b32_e32 v234, 16, v194
	v_and_b32_e32 v235, s28, v194
	v_lshlrev_b32_e32 v236, 16, v195
	v_and_b32_e32 v237, s28, v195
	v_add_f32_e32 v160, v160, v230
	v_add_f32_e32 v161, v161, v231
	v_add_f32_e32 v162, v162, v232
	v_add_f32_e32 v163, v163, v233
	v_add_f32_e32 v152, v152, v234
	v_add_f32_e32 v153, v153, v235
	v_add_f32_e32 v154, v154, v236
	v_add_f32_e32 v155, v155, v237
	v_cvt_pk_bf16_f32 v192, v160, v161
	v_cvt_pk_bf16_f32 v193, v162, v163
	v_cvt_pk_bf16_f32 v194, v152, v153
	v_cvt_pk_bf16_f32 v195, v154, v155
	global_store_dwordx4 v[214:215], v[192:195], off
	v_lshlrev_b32_e32 v230, 16, v188
	v_and_b32_e32 v231, s28, v188
	v_lshlrev_b32_e32 v232, 16, v189
	v_and_b32_e32 v233, s28, v189
	v_lshlrev_b32_e32 v234, 16, v190
	v_and_b32_e32 v235, s28, v190
	v_lshlrev_b32_e32 v236, 16, v191
	v_and_b32_e32 v237, s28, v191
	v_add_f32_e32 v144, v144, v230
	v_add_f32_e32 v145, v145, v231
	v_add_f32_e32 v146, v146, v232
	v_add_f32_e32 v147, v147, v233
	v_add_f32_e32 v136, v136, v234
	v_add_f32_e32 v137, v137, v235
	v_add_f32_e32 v138, v138, v236
	v_add_f32_e32 v139, v139, v237
	v_cvt_pk_bf16_f32 v188, v144, v145
	v_cvt_pk_bf16_f32 v189, v146, v147
	v_cvt_pk_bf16_f32 v190, v136, v137
	v_cvt_pk_bf16_f32 v191, v138, v139
	global_store_dwordx4 v[214:215], v[188:191], off offset:256
	v_mul_f32_e32 v230, v160, v160
	v_mul_f32_e32 v231, v161, v161
	v_mul_f32_e32 v232, v162, v162
	v_mul_f32_e32 v233, v163, v163
	v_fma_f32 v230, v152, v152, v230
	v_fma_f32 v231, v153, v153, v231
	v_fma_f32 v232, v154, v154, v232
	v_fma_f32 v233, v155, v155, v233
	v_fma_f32 v230, v144, v144, v230
	v_fma_f32 v231, v145, v145, v231
	v_fma_f32 v232, v146, v146, v232
	v_fma_f32 v233, v147, v147, v233
	v_fma_f32 v230, v136, v136, v230
	v_fma_f32 v231, v137, v137, v231
	v_fma_f32 v232, v138, v138, v232
	v_fma_f32 v233, v139, v139, v233
	v_add_f32_e32 v230, v230, v232
	v_add_f32_e32 v231, v231, v233
	v_add_f32_e32 v214, v230, v231
	s_waitcnt vmcnt(14)
	v_lshlrev_b32_e32 v230, 16, v184
	v_and_b32_e32 v231, s28, v184
	v_lshlrev_b32_e32 v232, 16, v185
	v_and_b32_e32 v233, s28, v185
	v_lshlrev_b32_e32 v234, 16, v186
	v_and_b32_e32 v235, s28, v186
	v_lshlrev_b32_e32 v236, 16, v187
	v_and_b32_e32 v237, s28, v187
	v_add_f32_e32 v120, v120, v230
	v_add_f32_e32 v121, v121, v231
	v_add_f32_e32 v122, v122, v232
	v_add_f32_e32 v123, v123, v233
	v_add_f32_e32 v116, v116, v234
	v_add_f32_e32 v117, v117, v235
	v_add_f32_e32 v118, v118, v236
	v_add_f32_e32 v119, v119, v237
	v_cvt_pk_bf16_f32 v184, v120, v121
	v_cvt_pk_bf16_f32 v185, v122, v123
	v_cvt_pk_bf16_f32 v186, v116, v117
	v_cvt_pk_bf16_f32 v187, v118, v119
	global_store_dwordx4 v[216:217], v[184:187], off
	v_lshlrev_b32_e32 v230, 16, v180
	v_and_b32_e32 v231, s28, v180
	v_lshlrev_b32_e32 v232, 16, v181
	v_and_b32_e32 v233, s28, v181
	v_lshlrev_b32_e32 v234, 16, v182
	v_and_b32_e32 v235, s28, v182
	v_lshlrev_b32_e32 v236, 16, v183
	v_and_b32_e32 v237, s28, v183
	v_add_f32_e32 v104, v104, v230
	v_add_f32_e32 v105, v105, v231
	v_add_f32_e32 v106, v106, v232
	v_add_f32_e32 v107, v107, v233
	v_add_f32_e32 v100, v100, v234
	v_add_f32_e32 v101, v101, v235
	v_add_f32_e32 v102, v102, v236
	v_add_f32_e32 v103, v103, v237
	v_cvt_pk_bf16_f32 v180, v104, v105
	v_cvt_pk_bf16_f32 v181, v106, v107
	v_cvt_pk_bf16_f32 v182, v100, v101
	v_cvt_pk_bf16_f32 v183, v102, v103
	global_store_dwordx4 v[216:217], v[180:183], off offset:256
	v_mul_f32_e32 v230, v120, v120
	v_mul_f32_e32 v231, v121, v121
	v_mul_f32_e32 v232, v122, v122
	v_mul_f32_e32 v233, v123, v123
	v_fma_f32 v230, v116, v116, v230
	v_fma_f32 v231, v117, v117, v231
	v_fma_f32 v232, v118, v118, v232
	v_fma_f32 v233, v119, v119, v233
	v_fma_f32 v230, v104, v104, v230
	v_fma_f32 v231, v105, v105, v231
	v_fma_f32 v232, v106, v106, v232
	v_fma_f32 v233, v107, v107, v233
	v_fma_f32 v230, v100, v100, v230
	v_fma_f32 v231, v101, v101, v231
	v_fma_f32 v232, v102, v102, v232
	v_fma_f32 v233, v103, v103, v233
	v_add_f32_e32 v230, v230, v232
	v_add_f32_e32 v231, v231, v233
	v_add_f32_e32 v216, v230, v231
	s_waitcnt vmcnt(14)
; __device__ __forceinline__ unsigned cvtpk(float lo, float hi) { f32x2 v = {lo, hi}; bf16x2_t b = __builtin_convertvector(v, bf16x2_t); return __builtin_bit_cast(unsigned, b); }
;     __device__ __forceinline__ void operator()(const f32x4 (&acc)[2][2][4][2], const Unit& u, int wr, int wc, int fr, int fq) const {
;     ...
;                 for (int bj = 0; bj < 2; ++bj) w[ai][m][bj] = *(const u32x4*)(xb + (size_t)(row0 + ai * HALF + m * 16) * 1024 + col0 + bj * HALF);
; #pragma unroll
;         for (int ai = 0; ai < 2; ++ai)
; #pragma unroll
;             for (int m = 0; m < 4; ++m) {
;                 const int row = row0 + ai * HALF + m * 16;
;                 const size_t off = (size_t)row * 1024 + col0;
;                 float ss = 0.f;
; #pragma unroll
;                 for (int bj = 0; bj < 2; ++bj) {
;                     const u32x4 wv = w[ai][m][bj];
;                     f32x4 o0 = acc[ai][bj][m][0], o1 = acc[ai][bj][m][1];
;                     o0[0] += __builtin_bit_cast(float, wv.x << 16); o0[1] += __builtin_bit_cast(float, wv.x & 0xffff0000u); o0[2] += __builtin_bit_cast(float, wv.y << 16); o0[3] += __builtin_bit_cast(float, wv.y & 0xffff0000u);
;                     o1[0] += __builtin_bit_cast(float, wv.z << 16); o1[1] += __builtin_bit_cast(float, wv.z & 0xffff0000u); o1[2] += __builtin_bit_cast(float, wv.w << 16); o1[3] += __builtin_bit_cast(float, wv.w & 0xffff0000u);
;                     if (last) { *(f32x4*)(out + off + bj * HALF) = o0; *(f32x4*)(out + off + bj * HALF + 4) = o1; }
;                     else {
;                         u32x4 v; v.x = cvtpk(o0[0], o0[1]); v.y = cvtpk(o0[2], o0[3]); v.z = cvtpk(o1[0], o1[1]); v.w = cvtpk(o1[2], o1[3]);
;                         *(u32x4*)(xb + off + bj * HALF) = v;
;                         ss += (o0[0] * o0[0] + o0[1] * o0[1]) + (o0[2] * o0[2] + o0[3] * o0[3]) + (o1[0] * o1[0] + o1[1] * o1[1]) + (o1[2] * o1[2] + o1[3] * o1[3]);
	v_lshlrev_b32_e32 v230, 16, v176
	v_and_b32_e32 v231, s28, v176
	v_lshlrev_b32_e32 v232, 16, v177
	v_and_b32_e32 v233, s28, v177
	v_lshlrev_b32_e32 v234, 16, v178
	v_and_b32_e32 v235, s28, v178
	v_lshlrev_b32_e32 v236, 16, v179
	v_and_b32_e32 v237, s28, v179
	v_add_f32_e32 v96, v96, v230
	v_add_f32_e32 v97, v97, v231
	v_add_f32_e32 v98, v98, v232
	v_add_f32_e32 v99, v99, v233
	v_add_f32_e32 v92, v92, v234
	v_add_f32_e32 v93, v93, v235
	v_add_f32_e32 v94, v94, v236
	v_add_f32_e32 v95, v95, v237
	v_cvt_pk_bf16_f32 v176, v96, v97
	v_cvt_pk_bf16_f32 v177, v98, v99
	v_cvt_pk_bf16_f32 v178, v92, v93
	v_cvt_pk_bf16_f32 v179, v94, v95
	global_store_dwordx4 v[218:219], v[176:179], off
	v_lshlrev_b32_e32 v230, 16, v172
	v_and_b32_e32 v231, s28, v172
	v_lshlrev_b32_e32 v232, 16, v173
	v_and_b32_e32 v233, s28, v173
	v_lshlrev_b32_e32 v234, 16, v174
	v_and_b32_e32 v235, s28, v174
	v_lshlrev_b32_e32 v236, 16, v175
	v_and_b32_e32 v237, s28, v175
	v_add_f32_e32 v88, v88, v230
	v_add_f32_e32 v89, v89, v231
	v_add_f32_e32 v90, v90, v232
	v_add_f32_e32 v91, v91, v233
	v_add_f32_e32 v84, v84, v234
	v_add_f32_e32 v85, v85, v235
	v_add_f32_e32 v86, v86, v236
	v_add_f32_e32 v87, v87, v237
	v_cvt_pk_bf16_f32 v172, v88, v89
	v_cvt_pk_bf16_f32 v173, v90, v91
	v_cvt_pk_bf16_f32 v174, v84, v85
	v_cvt_pk_bf16_f32 v175, v86, v87
	global_store_dwordx4 v[218:219], v[172:175], off offset:256
	v_mul_f32_e32 v230, v96, v96
	v_mul_f32_e32 v231, v97, v97
	v_mul_f32_e32 v232, v98, v98
	v_mul_f32_e32 v233, v99, v99
	v_fma_f32 v230, v92, v92, v230
	v_fma_f32 v231, v93, v93, v231
	v_fma_f32 v232, v94, v94, v232
	v_fma_f32 v233, v95, v95, v233
	v_fma_f32 v230, v88, v88, v230
	v_fma_f32 v231, v89, v89, v231
	v_fma_f32 v232, v90, v90, v232
	v_fma_f32 v233, v91, v91, v233
	v_fma_f32 v230, v84, v84, v230
	v_fma_f32 v231, v85, v85, v231
	v_fma_f32 v232, v86, v86, v232
	v_fma_f32 v233, v87, v87, v233
	v_add_f32_e32 v230, v230, v232
	v_add_f32_e32 v231, v231, v233
	v_add_f32_e32 v218, v230, v231
	s_waitcnt vmcnt(14)
	v_lshlrev_b32_e32 v230, 16, v168
	v_and_b32_e32 v231, s28, v168
	v_lshlrev_b32_e32 v232, 16, v169
	v_and_b32_e32 v233, s28, v169
	v_lshlrev_b32_e32 v234, 16, v170
	v_and_b32_e32 v235, s28, v170
	v_lshlrev_b32_e32 v236, 16, v171
	v_and_b32_e32 v237, s28, v171
	v_add_f32_e32 v80, v80, v230
	v_add_f32_e32 v81, v81, v231
	v_add_f32_e32 v82, v82, v232
	v_add_f32_e32 v83, v83, v233
	v_add_f32_e32 v76, v76, v234
	v_add_f32_e32 v77, v77, v235
	v_add_f32_e32 v78, v78, v236
	v_add_f32_e32 v79, v79, v237
	v_cvt_pk_bf16_f32 v168, v80, v81
	v_cvt_pk_bf16_f32 v169, v82, v83
	v_cvt_pk_bf16_f32 v170, v76, v77
	v_cvt_pk_bf16_f32 v171, v78, v79
	global_store_dwordx4 v[220:221], v[168:171], off
	v_lshlrev_b32_e32 v230, 16, v164
	v_and_b32_e32 v231, s28, v164
	v_lshlrev_b32_e32 v232, 16, v165
	v_and_b32_e32 v233, s28, v165
	v_lshlrev_b32_e32 v234, 16, v166
	v_and_b32_e32 v235, s28, v166
	v_lshlrev_b32_e32 v236, 16, v167
	v_and_b32_e32 v237, s28, v167
	v_add_f32_e32 v72, v72, v230
	v_add_f32_e32 v73, v73, v231
	v_add_f32_e32 v74, v74, v232
	v_add_f32_e32 v75, v75, v233
	v_add_f32_e32 v68, v68, v234
	v_add_f32_e32 v69, v69, v235
	v_add_f32_e32 v70, v70, v236
	v_add_f32_e32 v71, v71, v237
	v_cvt_pk_bf16_f32 v164, v72, v73
	v_cvt_pk_bf16_f32 v165, v74, v75
	v_cvt_pk_bf16_f32 v166, v68, v69
	v_cvt_pk_bf16_f32 v167, v70, v71
	global_store_dwordx4 v[220:221], v[164:167], off offset:256
	v_mul_f32_e32 v230, v80, v80
	v_mul_f32_e32 v231, v81, v81
	v_mul_f32_e32 v232, v82, v82
	v_mul_f32_e32 v233, v83, v83
	v_fma_f32 v230, v76, v76, v230
	v_fma_f32 v231, v77, v77, v231
	v_fma_f32 v232, v78, v78, v232
	v_fma_f32 v233, v79, v79, v233
	v_fma_f32 v230, v72, v72, v230
	v_fma_f32 v231, v73, v73, v231
	v_fma_f32 v232, v74, v74, v232
	v_fma_f32 v233, v75, v75, v233
	v_fma_f32 v230, v68, v68, v230
	v_fma_f32 v231, v69, v69, v231
	v_fma_f32 v232, v70, v70, v232
	v_fma_f32 v233, v71, v71, v233
	v_add_f32_e32 v230, v230, v232
	v_add_f32_e32 v231, v231, v233
	v_add_f32_e32 v220, v230, v231
	s_waitcnt vmcnt(14)
	v_lshlrev_b32_e32 v230, 16, v156
	v_and_b32_e32 v231, s28, v156
	v_lshlrev_b32_e32 v232, 16, v157
	v_and_b32_e32 v233, s28, v157
	v_lshlrev_b32_e32 v234, 16, v158
	v_and_b32_e32 v235, s28, v158
	v_lshlrev_b32_e32 v236, 16, v159
	v_and_b32_e32 v237, s28, v159
	v_add_f32_e32 v64, v64, v230
	v_add_f32_e32 v65, v65, v231
	v_add_f32_e32 v66, v66, v232
	v_add_f32_e32 v67, v67, v233
	v_add_f32_e32 v60, v60, v234
	v_add_f32_e32 v61, v61, v235
	v_add_f32_e32 v62, v62, v236
	v_add_f32_e32 v63, v63, v237
	v_cvt_pk_bf16_f32 v156, v64, v65
	v_cvt_pk_bf16_f32 v157, v66, v67
	v_cvt_pk_bf16_f32 v158, v60, v61
	v_cvt_pk_bf16_f32 v159, v62, v63
	global_store_dwordx4 v[222:223], v[156:159], off
	v_lshlrev_b32_e32 v230, 16, v148
	v_and_b32_e32 v231, s28, v148
	v_lshlrev_b32_e32 v232, 16, v149
	v_and_b32_e32 v233, s28, v149
	v_lshlrev_b32_e32 v234, 16, v150
	v_and_b32_e32 v235, s28, v150
	v_lshlrev_b32_e32 v236, 16, v151
	v_and_b32_e32 v237, s28, v151
	v_add_f32_e32 v56, v56, v230
	v_add_f32_e32 v57, v57, v231
	v_add_f32_e32 v58, v58, v232
	v_add_f32_e32 v59, v59, v233
	v_add_f32_e32 v52, v52, v234
	v_add_f32_e32 v53, v53, v235
	v_add_f32_e32 v54, v54, v236
	v_add_f32_e32 v55, v55, v237
	v_cvt_pk_bf16_f32 v148, v56, v57
	v_cvt_pk_bf16_f32 v149, v58, v59
	v_cvt_pk_bf16_f32 v150, v52, v53
	v_cvt_pk_bf16_f32 v151, v54, v55
	global_store_dwordx4 v[222:223], v[148:151], off offset:256
	v_mul_f32_e32 v230, v64, v64
	v_mul_f32_e32 v231, v65, v65
	v_mul_f32_e32 v232, v66, v66
	v_mul_f32_e32 v233, v67, v67
	v_fma_f32 v230, v60, v60, v230
	v_fma_f32 v231, v61, v61, v231
	v_fma_f32 v232, v62, v62, v232
	v_fma_f32 v233, v63, v63, v233
	v_fma_f32 v230, v56, v56, v230
	v_fma_f32 v231, v57, v57, v231
	v_fma_f32 v232, v58, v58, v232
	v_fma_f32 v233, v59, v59, v233
	v_fma_f32 v230, v52, v52, v230
	v_fma_f32 v231, v53, v53, v231
	v_fma_f32 v232, v54, v54, v232
	v_fma_f32 v233, v55, v55, v233
	v_add_f32_e32 v230, v230, v232
	v_add_f32_e32 v231, v231, v233
	v_add_f32_e32 v222, v230, v231
	s_waitcnt vmcnt(14)
; __device__ __forceinline__ unsigned cvtpk(float lo, float hi) { f32x2 v = {lo, hi}; bf16x2_t b = __builtin_convertvector(v, bf16x2_t); return __builtin_bit_cast(unsigned, b); }
;     __device__ __forceinline__ void operator()(const f32x4 (&acc)[2][2][4][2], const Unit& u, int wr, int wc, int fr, int fq) const {
;     ...
;                     const u32x4 wv = w[ai][m][bj];
;                     f32x4 o0 = acc[ai][bj][m][0], o1 = acc[ai][bj][m][1];
;                     o0[0] += __builtin_bit_cast(float, wv.x << 16); o0[1] += __builtin_bit_cast(float, wv.x & 0xffff0000u); o0[2] += __builtin_bit_cast(float, wv.y << 16); o0[3] += __builtin_bit_cast(float, wv.y & 0xffff0000u);
;                     o1[0] += __builtin_bit_cast(float, wv.z << 16); o1[1] += __builtin_bit_cast(float, wv.z & 0xffff0000u); o1[2] += __builtin_bit_cast(float, wv.w << 16); o1[3] += __builtin_bit_cast(float, wv.w & 0xffff0000u);
;                     if (last) { *(f32x4*)(out + off + bj * HALF) = o0; *(f32x4*)(out + off + bj * HALF + 4) = o1; }
;                     else {
;                         u32x4 v; v.x = cvtpk(o0[0], o0[1]); v.y = cvtpk(o0[2], o0[3]); v.z = cvtpk(o1[0], o1[1]); v.w = cvtpk(o1[2], o1[3]);
;                         *(u32x4*)(xb + off + bj * HALF) = v;
;                         ss += (o0[0] * o0[0] + o0[1] * o0[1]) + (o0[2] * o0[2] + o0[3] * o0[3]) + (o1[0] * o1[0] + o1[1] * o1[1]) + (o1[2] * o1[2] + o1[3] * o1[3]);
;                     }
;                 }
;                 if (!last) {
;                     ss += __shfl_xor(ss, 16); ss += __shfl_xor(ss, 32);
;                     if (fq == 0) ssq_out[(size_t)row * 16 + 4 * u.pn + wc] = ss;
	v_lshlrev_b32_e32 v230, 16, v140
	v_and_b32_e32 v231, s28, v140
	v_lshlrev_b32_e32 v232, 16, v141
	v_and_b32_e32 v233, s28, v141
	v_lshlrev_b32_e32 v234, 16, v142
	v_and_b32_e32 v235, s28, v142
	v_lshlrev_b32_e32 v236, 16, v143
	v_and_b32_e32 v237, s28, v143
	v_add_f32_e32 v48, v48, v230
	v_add_f32_e32 v49, v49, v231
	v_add_f32_e32 v50, v50, v232
	v_add_f32_e32 v51, v51, v233
	v_add_f32_e32 v44, v44, v234
	v_add_f32_e32 v45, v45, v235
	v_add_f32_e32 v46, v46, v236
	v_add_f32_e32 v47, v47, v237
	v_cvt_pk_bf16_f32 v140, v48, v49
	v_cvt_pk_bf16_f32 v141, v50, v51
	v_cvt_pk_bf16_f32 v142, v44, v45
	v_cvt_pk_bf16_f32 v143, v46, v47
	global_store_dwordx4 v[224:225], v[140:143], off
	v_lshlrev_b32_e32 v230, 16, v132
	v_and_b32_e32 v231, s28, v132
	v_lshlrev_b32_e32 v232, 16, v133
	v_and_b32_e32 v233, s28, v133
	v_lshlrev_b32_e32 v234, 16, v134
	v_and_b32_e32 v235, s28, v134
	v_lshlrev_b32_e32 v236, 16, v135
	v_and_b32_e32 v237, s28, v135
	v_add_f32_e32 v40, v40, v230
	v_add_f32_e32 v41, v41, v231
	v_add_f32_e32 v42, v42, v232
	v_add_f32_e32 v43, v43, v233
	v_add_f32_e32 v36, v36, v234
	v_add_f32_e32 v37, v37, v235
	v_add_f32_e32 v38, v38, v236
	v_add_f32_e32 v39, v39, v237
	v_cvt_pk_bf16_f32 v132, v40, v41
	v_cvt_pk_bf16_f32 v133, v42, v43
	v_cvt_pk_bf16_f32 v134, v36, v37
	v_cvt_pk_bf16_f32 v135, v38, v39
	global_store_dwordx4 v[224:225], v[132:135], off offset:256
	v_mul_f32_e32 v230, v48, v48
	v_mul_f32_e32 v231, v49, v49
	v_mul_f32_e32 v232, v50, v50
	v_mul_f32_e32 v233, v51, v51
	v_fma_f32 v230, v44, v44, v230
	v_fma_f32 v231, v45, v45, v231
	v_fma_f32 v232, v46, v46, v232
	v_fma_f32 v233, v47, v47, v233
	v_fma_f32 v230, v40, v40, v230
	v_fma_f32 v231, v41, v41, v231
	v_fma_f32 v232, v42, v42, v232
	v_fma_f32 v233, v43, v43, v233
	v_fma_f32 v230, v36, v36, v230
	v_fma_f32 v231, v37, v37, v231
	v_fma_f32 v232, v38, v38, v232
	v_fma_f32 v233, v39, v39, v233
	v_add_f32_e32 v230, v230, v232
	v_add_f32_e32 v231, v231, v233
	v_add_f32_e32 v224, v230, v231
	s_waitcnt vmcnt(14)
	v_lshlrev_b32_e32 v230, 16, v128
	v_and_b32_e32 v231, s28, v128
	v_lshlrev_b32_e32 v232, 16, v129
	v_and_b32_e32 v233, s28, v129
	v_lshlrev_b32_e32 v234, 16, v130
	v_and_b32_e32 v235, s28, v130
	v_lshlrev_b32_e32 v236, 16, v131
	v_and_b32_e32 v237, s28, v131
	v_add_f32_e32 v32, v32, v230
	v_add_f32_e32 v33, v33, v231
	v_add_f32_e32 v34, v34, v232
	v_add_f32_e32 v35, v35, v233
	v_add_f32_e32 v28, v28, v234
	v_add_f32_e32 v29, v29, v235
	v_add_f32_e32 v30, v30, v236
	v_add_f32_e32 v31, v31, v237
	v_cvt_pk_bf16_f32 v128, v32, v33
	v_cvt_pk_bf16_f32 v129, v34, v35
	v_cvt_pk_bf16_f32 v130, v28, v29
	v_cvt_pk_bf16_f32 v131, v30, v31
	global_store_dwordx4 v[226:227], v[128:131], off
	v_lshlrev_b32_e32 v230, 16, v112
	v_and_b32_e32 v231, s28, v112
	v_lshlrev_b32_e32 v232, 16, v113
	v_and_b32_e32 v233, s28, v113
	v_lshlrev_b32_e32 v234, 16, v114
	v_and_b32_e32 v235, s28, v114
	v_lshlrev_b32_e32 v236, 16, v115
	v_and_b32_e32 v237, s28, v115
	v_add_f32_e32 v24, v24, v230
	v_add_f32_e32 v25, v25, v231
	v_add_f32_e32 v26, v26, v232
	v_add_f32_e32 v27, v27, v233
	v_add_f32_e32 v20, v20, v234
	v_add_f32_e32 v21, v21, v235
	v_add_f32_e32 v22, v22, v236
	v_add_f32_e32 v23, v23, v237
	v_cvt_pk_bf16_f32 v112, v24, v25
	v_cvt_pk_bf16_f32 v113, v26, v27
	v_cvt_pk_bf16_f32 v114, v20, v21
	v_cvt_pk_bf16_f32 v115, v22, v23
	global_store_dwordx4 v[226:227], v[112:115], off offset:256
	v_mul_f32_e32 v230, v32, v32
	v_mul_f32_e32 v231, v33, v33
	v_mul_f32_e32 v232, v34, v34
	v_mul_f32_e32 v233, v35, v35
	v_fma_f32 v230, v28, v28, v230
	v_fma_f32 v231, v29, v29, v231
	v_fma_f32 v232, v30, v30, v232
	v_fma_f32 v233, v31, v31, v233
	v_fma_f32 v230, v24, v24, v230
	v_fma_f32 v231, v25, v25, v231
	v_fma_f32 v232, v26, v26, v232
	v_fma_f32 v233, v27, v27, v233
	v_fma_f32 v230, v20, v20, v230
	v_fma_f32 v231, v21, v21, v231
	v_fma_f32 v232, v22, v22, v232
	v_fma_f32 v233, v23, v23, v233
	v_add_f32_e32 v230, v230, v232
	v_add_f32_e32 v231, v231, v233
	v_add_f32_e32 v226, v230, v231
	s_waitcnt vmcnt(14)
	v_lshlrev_b32_e32 v230, 16, v124
	v_and_b32_e32 v231, s28, v124
	v_lshlrev_b32_e32 v232, 16, v125
	v_and_b32_e32 v233, s28, v125
	v_lshlrev_b32_e32 v234, 16, v126
	v_and_b32_e32 v235, s28, v126
	v_lshlrev_b32_e32 v236, 16, v127
	v_and_b32_e32 v237, s28, v127
	v_add_f32_e32 v16, v16, v230
	v_add_f32_e32 v17, v17, v231
	v_add_f32_e32 v18, v18, v232
	v_add_f32_e32 v19, v19, v233
	v_add_f32_e32 v12, v12, v234
	v_add_f32_e32 v13, v13, v235
	v_add_f32_e32 v14, v14, v236
	v_add_f32_e32 v15, v15, v237
	v_cvt_pk_bf16_f32 v124, v16, v17
	v_cvt_pk_bf16_f32 v125, v18, v19
	v_cvt_pk_bf16_f32 v126, v12, v13
	v_cvt_pk_bf16_f32 v127, v14, v15
	global_store_dwordx4 v[228:229], v[124:127], off
	v_lshlrev_b32_e32 v230, 16, v108
	v_and_b32_e32 v231, s28, v108
	v_lshlrev_b32_e32 v232, 16, v109
	v_and_b32_e32 v233, s28, v109
	v_lshlrev_b32_e32 v234, 16, v110
	v_and_b32_e32 v235, s28, v110
	v_lshlrev_b32_e32 v236, 16, v111
	v_and_b32_e32 v237, s28, v111
	v_add_f32_e32 v8, v8, v230
	v_add_f32_e32 v9, v9, v231
	v_add_f32_e32 v10, v10, v232
	v_add_f32_e32 v11, v11, v233
	v_add_f32_e32 v4, v4, v234
	v_add_f32_e32 v5, v5, v235
	v_add_f32_e32 v6, v6, v236
	v_add_f32_e32 v7, v7, v237
	v_cvt_pk_bf16_f32 v108, v8, v9
	v_cvt_pk_bf16_f32 v109, v10, v11
	v_cvt_pk_bf16_f32 v110, v4, v5
	v_cvt_pk_bf16_f32 v111, v6, v7
	global_store_dwordx4 v[228:229], v[108:111], off offset:256
	v_mul_f32_e32 v230, v16, v16
	v_mul_f32_e32 v231, v17, v17
	v_mul_f32_e32 v232, v18, v18
	v_mul_f32_e32 v233, v19, v19
	v_fma_f32 v230, v12, v12, v230
	v_fma_f32 v231, v13, v13, v231
	v_fma_f32 v232, v14, v14, v232
	v_fma_f32 v233, v15, v15, v233
	v_fma_f32 v230, v8, v8, v230
	v_fma_f32 v231, v9, v9, v231
	v_fma_f32 v232, v10, v10, v232
	v_fma_f32 v233, v11, v11, v233
	v_fma_f32 v230, v4, v4, v230
	v_fma_f32 v231, v5, v5, v231
	v_fma_f32 v232, v6, v6, v232
	v_fma_f32 v233, v7, v7, v233
	v_add_f32_e32 v230, v230, v232
	v_add_f32_e32 v231, v231, v233
	v_add_f32_e32 v228, v230, v231
	s_nop 1
	v_permlane32_swap_b32_e32 v214, v216
	v_permlane32_swap_b32_e32 v218, v220
	v_permlane32_swap_b32_e32 v222, v224
	v_permlane32_swap_b32_e32 v226, v228
	v_add_f32_e32 v214, v214, v216
	v_add_f32_e32 v218, v218, v220
	v_add_f32_e32 v222, v222, v224
	v_add_f32_e32 v226, v226, v228
	s_nop 1
	v_permlane16_swap_b32_e32 v214, v218
	v_permlane16_swap_b32_e32 v222, v226
	v_add_f32_e32 v214, v214, v218
	v_add_f32_e32 v222, v222, v226
	v_bfe_u32 v230, v250, 4, 1
	v_bfe_u32 v231, v250, 5, 1
	v_lshl_or_b32 v230, v230, 1, v231
	v_lshlrev_b32_e32 v232, 6, v212
	v_lshl_add_u32 v232, v230, 10, v232
	s_lshl_b32 s29, s24, 4
	s_lshl_b32 s27, s48, 2
	s_add_i32 s29, s29, s27
	v_add_u32_e32 v232, s29, v232
	v_mov_b32_e32 v233, v2
	v_lshl_add_u64 v[232:233], s[12:13], 0, v[232:233]
	s_mov_b32 s100, 0x2000
	v_lshl_add_u64 v[234:235], v[232:233], 0, s[100:101]
	global_store_dword v[232:233], v214, off
	global_store_dword v[234:235], v222, off
	s_andn2_b64 vcc, exec, s[6:7]
	s_mov_b64 s[6:7], -1
	s_cbranch_vccnz .LBB0_321
; #define PG8_BAR __builtin_amdgcn_s_barrier()
; template <class Epi, class Sched, bool ALIGN_EPI = false, bool SP2 = false>
; __device__ __forceinline__ void gemm_phase(PG8_LAS unsigned char* lds, const Gemm g, const Sched& S, const Epi& E) {
;     ...
;         if (!has_next) break;
; #pragma unroll
;         for (int a = 0; a < 2; ++a)
; #pragma unroll
;             for (int b = 0; b < 2; ++b)
; #pragma unroll
;                 for (int m = 0; m < 4; ++m)
; #pragma unroll
;                     for (int n = 0; n < 2; ++n) acc[a][b][m][n] = (f32x4){0.f, 0.f, 0.f, 0.f};
;         cur = nxt; cA = nA; cB = nB; ++ui;
;         if constexpr (ALIGN_EPI) { if (wr == 1) PG8_BAR; }
	s_andn2_b64 vcc, exec, s[8:9]
	s_cbranch_vccnz .LBB0_320
	s_barrier
	s_branch .LBB0_320

; __device__ __forceinline__ unsigned cvtpk(float lo, float hi) { f32x2 v = {lo, hi}; bf16x2_t b = __builtin_convertvector(v, bf16x2_t); return __builtin_bit_cast(unsigned, b); }
;     __device__ __forceinline__ void operator()(const f32x4 (&acc)[2][2][4][2], const Unit& u, int wr, int wc, int fr, int fq) const {
;     ...
;         float rs[2][4]; load_rstd(ssq, row0, fq, rs);
; #pragma unroll
;         for (int ai = 0; ai < 2; ++ai)
; #pragma unroll
;             for (int m = 0; m < 4; ++m) {
;                 const float mul = rs[ai][m], nml = -mul * LOG2E_F, mul2 = mul * mul;
;                 float hv[8];
; #pragma unroll
;                 for (int n = 0; n < 2; ++n)
; #pragma unroll
;                     for (int i = 0; i < 4; ++i) {
;                         const float ag = acc[ai][0][m][n][i];
;                         const float e = __builtin_amdgcn_exp2f(ag * nml);
;                         hv[4 * n + i] = (ag * acc[ai][1][m][n][i]) * (mul2 * __builtin_amdgcn_rcpf(1.0f + e));
;                     }
;                 u32x4 w; w.x = cvtpk(hv[0], hv[1]); w.y = cvtpk(hv[2], hv[3]); w.z = cvtpk(hv[4], hv[5]); w.w = cvtpk(hv[6], hv[7]);
;                 *(u32x4*)(H + (size_t)(row0 + ai * HALF + m * 16) * 2816 + col0) = w;
.LBB0_408:
	v_lshl_add_u32 v144, s6, 8, v3
	v_lshlrev_b32_e32 v146, 6, v144
	v_mov_b32_e32 v147, v2
	v_lshl_add_u64 v[148:149], v[138:139], 0, v[146:147]
	s_mov_b32 s100, 0x2000
	s_mov_b32 s101, 0
	v_lshl_add_u64 v[150:151], v[148:149], 0, s[100:101]
	global_load_dwordx4 v[168:171], v[148:149], off
	global_load_dwordx4 v[172:175], v[148:149], off offset:1024
	global_load_dwordx4 v[176:179], v[148:149], off offset:2048
	global_load_dwordx4 v[180:183], v[148:149], off offset:3072
	global_load_dwordx4 v[184:187], v[150:151], off
	global_load_dwordx4 v[188:191], v[150:151], off offset:1024
	global_load_dwordx4 v[192:195], v[150:151], off offset:2048
	global_load_dwordx4 v[202:205], v[150:151], off offset:3072
	v_mov_b64_e32 v[146:147], s[12:13]
	v_lshl_or_b32 v145, s3, 7, v165
	v_mad_i64_i32 v[226:227], s[6:7], v144, s88, v[146:147]
	v_lshlrev_b32_e32 v228, 1, v145
	v_mov_b32_e32 v229, v2
	v_lshl_add_u64 v[226:227], v[226:227], 0, v[228:229]
	v_mov_b32_e32 v147, 0x358637bd
	v_mul_f32_e32 v124, v128, v124
	v_mul_f32_e32 v125, v129, v125
	v_mul_f32_e32 v126, v130, v126
	v_mul_f32_e32 v127, v131, v127
	v_mul_f32_e32 v116, v120, v116
	v_mul_f32_e32 v117, v121, v117
	v_mul_f32_e32 v118, v122, v118
	v_mul_f32_e32 v119, v123, v119
	v_mul_f32_e32 v108, v112, v108
	v_mul_f32_e32 v109, v113, v109
	v_mul_f32_e32 v110, v114, v110
	v_mul_f32_e32 v111, v115, v111
	v_mul_f32_e32 v100, v104, v100
	v_mul_f32_e32 v101, v105, v101
	v_mul_f32_e32 v102, v106, v102
	v_mul_f32_e32 v103, v107, v103
	v_mul_f32_e32 v92, v96, v92
	v_mul_f32_e32 v93, v97, v93
	v_mul_f32_e32 v94, v98, v94
	v_mul_f32_e32 v95, v99, v95
	v_mul_f32_e32 v84, v88, v84
	v_mul_f32_e32 v85, v89, v85
	v_mul_f32_e32 v86, v90, v86
	v_mul_f32_e32 v87, v91, v87
	v_mul_f32_e32 v76, v80, v76
	v_mul_f32_e32 v77, v81, v77
	v_mul_f32_e32 v78, v82, v78
	v_mul_f32_e32 v79, v83, v79
	v_mul_f32_e32 v68, v72, v68
	v_mul_f32_e32 v69, v73, v69
	v_mul_f32_e32 v70, v74, v70
	v_mul_f32_e32 v71, v75, v71
	v_mul_f32_e32 v60, v64, v60
	v_mul_f32_e32 v61, v65, v61
	v_mul_f32_e32 v62, v66, v62
	v_mul_f32_e32 v63, v67, v63
	v_mul_f32_e32 v52, v56, v52
	v_mul_f32_e32 v53, v57, v53
	v_mul_f32_e32 v54, v58, v54
	v_mul_f32_e32 v55, v59, v55
	v_mul_f32_e32 v44, v48, v44
	v_mul_f32_e32 v45, v49, v45
	v_mul_f32_e32 v46, v50, v46
	v_mul_f32_e32 v47, v51, v47
	v_mul_f32_e32 v36, v40, v36
	v_mul_f32_e32 v37, v41, v37
	v_mul_f32_e32 v38, v42, v38
	v_mul_f32_e32 v39, v43, v39
	v_mul_f32_e32 v28, v32, v28
	v_mul_f32_e32 v29, v33, v29
	v_mul_f32_e32 v30, v34, v30
	v_mul_f32_e32 v31, v35, v31
	v_mul_f32_e32 v20, v24, v20
	v_mul_f32_e32 v21, v25, v21
	v_mul_f32_e32 v22, v26, v22
	v_mul_f32_e32 v23, v27, v23
	v_mul_f32_e32 v12, v16, v12
	v_mul_f32_e32 v13, v17, v13
	v_mul_f32_e32 v14, v18, v14
	v_mul_f32_e32 v15, v19, v15
	v_mul_f32_e32 v4, v8, v4
	v_mul_f32_e32 v5, v9, v5
	v_mul_f32_e32 v6, v10, v6
	v_mul_f32_e32 v7, v11, v7
	s_waitcnt vmcnt(7)
	v_add_f32_e32 v152, v168, v169
	v_add_f32_e32 v170, v170, v171
	v_add_f32_e32 v152, v152, v170
	s_waitcnt vmcnt(6)
	v_add_f32_e32 v153, v172, v173
	v_add_f32_e32 v174, v174, v175
	v_add_f32_e32 v153, v153, v174
	s_waitcnt vmcnt(5)
	v_add_f32_e32 v154, v176, v177
	v_add_f32_e32 v178, v178, v179
	v_add_f32_e32 v154, v154, v178
	s_waitcnt vmcnt(4)
	v_add_f32_e32 v155, v180, v181
	v_add_f32_e32 v182, v182, v183
	v_add_f32_e32 v155, v155, v182
	s_waitcnt vmcnt(3)
	v_add_f32_e32 v156, v184, v185
	v_add_f32_e32 v186, v186, v187
	v_add_f32_e32 v156, v156, v186
	s_waitcnt vmcnt(2)
	v_add_f32_e32 v157, v188, v189
	v_add_f32_e32 v190, v190, v191
	v_add_f32_e32 v157, v157, v190
	s_waitcnt vmcnt(1)
	v_add_f32_e32 v158, v192, v193
	v_add_f32_e32 v194, v194, v195
	v_add_f32_e32 v158, v158, v194
	s_waitcnt vmcnt(0)
	v_add_f32_e32 v159, v202, v203
	v_add_f32_e32 v204, v204, v205
	v_add_f32_e32 v159, v159, v204
	s_nop 1
	v_permlane32_swap_b32_e32 v152, v153
	v_permlane32_swap_b32_e32 v154, v155
	v_permlane32_swap_b32_e32 v156, v157
	v_permlane32_swap_b32_e32 v158, v159
	v_add_f32_e32 v152, v152, v153
	v_add_f32_e32 v154, v154, v155
	v_add_f32_e32 v156, v156, v157
	v_add_f32_e32 v158, v158, v159
	s_nop 1
	v_permlane16_swap_b32_e32 v152, v154
	v_permlane16_swap_b32_e32 v156, v158
	v_add_f32_e32 v152, v152, v154
	v_add_f32_e32 v156, v156, v158
	v_fmamk_f32 v160, v152, 0x3a800000, v147
	v_fmamk_f32 v161, v156, 0x3a800000, v147
	v_rsq_f32_e32 v162, v160
	v_rsq_f32_e32 v163, v161
	s_nop 0
	v_mul_f32_e32 v162, 0xbfb8aa3b, v162
	v_mul_f32_e32 v163, 0xbfb8aa3b, v163
	v_mov_b32_e32 v146, v160
	s_nop 1
	v_permlane16_swap_b32_e32 v160, v146
	v_mov_b32_e32 v202, v160
	v_mov_b32_e32 v204, v146
	v_mov_b32_e32 v203, v160
	v_mov_b32_e32 v205, v146
	s_nop 1
	v_permlane32_swap_b32_e32 v202, v203
	v_permlane32_swap_b32_e32 v204, v205
	v_mov_b32_e32 v146, v161
	s_nop 1
	v_permlane16_swap_b32_e32 v161, v146
	v_mov_b32_e32 v206, v161
	v_mov_b32_e32 v208, v146
	v_mov_b32_e32 v207, v161
	v_mov_b32_e32 v209, v146
	s_nop 1
	v_permlane32_swap_b32_e32 v206, v207
	v_permlane32_swap_b32_e32 v208, v209
	v_mov_b32_e32 v146, v162
	s_nop 1
	v_permlane16_swap_b32_e32 v162, v146
	v_mov_b32_e32 v210, v162
	v_mov_b32_e32 v212, v146
	v_mov_b32_e32 v211, v162
	v_mov_b32_e32 v213, v146
	s_nop 1
	v_permlane32_swap_b32_e32 v210, v211
	v_permlane32_swap_b32_e32 v212, v213
	v_mov_b32_e32 v146, v163
	s_nop 1
	v_permlane16_swap_b32_e32 v163, v146
	v_mov_b32_e32 v214, v163
	v_mov_b32_e32 v216, v146
	v_mov_b32_e32 v215, v163
	v_mov_b32_e32 v217, v146
	s_nop 1
	v_permlane32_swap_b32_e32 v214, v215
	v_permlane32_swap_b32_e32 v216, v217
	v_mul_f32_e32 v218, v128, v210
	v_mul_f32_e32 v219, v129, v210
	v_mul_f32_e32 v220, v130, v210
	v_mul_f32_e32 v221, v131, v210
; __device__ __forceinline__ unsigned cvtpk(float lo, float hi) { f32x2 v = {lo, hi}; bf16x2_t b = __builtin_convertvector(v, bf16x2_t); return __builtin_bit_cast(unsigned, b); }
;     __device__ __forceinline__ void operator()(const f32x4 (&acc)[2][2][4][2], const Unit& u, int wr, int wc, int fr, int fq) const {
;     ...
;                     for (int i = 0; i < 4; ++i) {
;                         const float ag = acc[ai][0][m][n][i];
;                         const float e = __builtin_amdgcn_exp2f(ag * nml);
;                         hv[4 * n + i] = (ag * acc[ai][1][m][n][i]) * (mul2 * __builtin_amdgcn_rcpf(1.0f + e));
;                     }
;                 u32x4 w; w.x = cvtpk(hv[0], hv[1]); w.y = cvtpk(hv[2], hv[3]); w.z = cvtpk(hv[4], hv[5]); w.w = cvtpk(hv[6], hv[7]);
;                 *(u32x4*)(H + (size_t)(row0 + ai * HALF + m * 16) * 2816 + col0) = w;
	v_mul_f32_e32 v222, v120, v210
	v_mul_f32_e32 v223, v121, v210
	v_mul_f32_e32 v224, v122, v210
	v_mul_f32_e32 v225, v123, v210
	v_exp_f32_e32 v218, v218
	v_exp_f32_e32 v219, v219
	v_exp_f32_e32 v220, v220
	v_exp_f32_e32 v221, v221
	v_exp_f32_e32 v222, v222
	v_exp_f32_e32 v223, v223
	v_exp_f32_e32 v224, v224
	v_exp_f32_e32 v225, v225
	s_mov_b32 s100, 0x0
	v_lshl_add_u64 v[228:229], v[226:227], 0, s[100:101]
	v_fma_f32 v218, v218, v202, v202
	v_fma_f32 v219, v219, v202, v202
	v_fma_f32 v220, v220, v202, v202
	v_fma_f32 v221, v221, v202, v202
	v_fma_f32 v222, v222, v202, v202
	v_fma_f32 v223, v223, v202, v202
	v_fma_f32 v224, v224, v202, v202
	v_fma_f32 v225, v225, v202, v202
	v_rcp_f32_e32 v218, v218
	v_rcp_f32_e32 v219, v219
	v_rcp_f32_e32 v220, v220
	v_rcp_f32_e32 v221, v221
	v_rcp_f32_e32 v222, v222
	v_rcp_f32_e32 v223, v223
	v_rcp_f32_e32 v224, v224
	v_rcp_f32_e32 v225, v225
	s_nop 0
	v_mul_f32_e32 v124, v124, v218
	v_mul_f32_e32 v125, v125, v219
	v_mul_f32_e32 v126, v126, v220
	v_mul_f32_e32 v127, v127, v221
	v_mul_f32_e32 v116, v116, v222
	v_mul_f32_e32 v117, v117, v223
	v_mul_f32_e32 v118, v118, v224
	v_mul_f32_e32 v119, v119, v225
	v_cvt_pk_bf16_f32 v120, v124, v125
	v_cvt_pk_bf16_f32 v121, v126, v127
	v_cvt_pk_bf16_f32 v122, v116, v117
	v_cvt_pk_bf16_f32 v123, v118, v119
	global_store_dwordx4 v[228:229], v[120:123], off
	v_mul_f32_e32 v218, v112, v211
	v_mul_f32_e32 v219, v113, v211
	v_mul_f32_e32 v220, v114, v211
	v_mul_f32_e32 v221, v115, v211
	v_mul_f32_e32 v222, v104, v211
	v_mul_f32_e32 v223, v105, v211
	v_mul_f32_e32 v224, v106, v211
	v_mul_f32_e32 v225, v107, v211
	v_exp_f32_e32 v218, v218
	v_exp_f32_e32 v219, v219
	v_exp_f32_e32 v220, v220
	v_exp_f32_e32 v221, v221
	v_exp_f32_e32 v222, v222
	v_exp_f32_e32 v223, v223
	v_exp_f32_e32 v224, v224
	v_exp_f32_e32 v225, v225
	s_mov_b32 s100, 0x16000
	v_lshl_add_u64 v[228:229], v[226:227], 0, s[100:101]
	v_fma_f32 v218, v218, v203, v203
	v_fma_f32 v219, v219, v203, v203
	v_fma_f32 v220, v220, v203, v203
	v_fma_f32 v221, v221, v203, v203
	v_fma_f32 v222, v222, v203, v203
	v_fma_f32 v223, v223, v203, v203
	v_fma_f32 v224, v224, v203, v203
	v_fma_f32 v225, v225, v203, v203
	v_rcp_f32_e32 v218, v218
	v_rcp_f32_e32 v219, v219
	v_rcp_f32_e32 v220, v220
	v_rcp_f32_e32 v221, v221
	v_rcp_f32_e32 v222, v222
	v_rcp_f32_e32 v223, v223
	v_rcp_f32_e32 v224, v224
	v_rcp_f32_e32 v225, v225
	s_nop 0
	v_mul_f32_e32 v108, v108, v218
	v_mul_f32_e32 v109, v109, v219
	v_mul_f32_e32 v110, v110, v220
	v_mul_f32_e32 v111, v111, v221
	v_mul_f32_e32 v100, v100, v222
	v_mul_f32_e32 v101, v101, v223
	v_mul_f32_e32 v102, v102, v224
	v_mul_f32_e32 v103, v103, v225
	v_cvt_pk_bf16_f32 v104, v108, v109
	v_cvt_pk_bf16_f32 v105, v110, v111
	v_cvt_pk_bf16_f32 v106, v100, v101
	v_cvt_pk_bf16_f32 v107, v102, v103
	global_store_dwordx4 v[228:229], v[104:107], off
	v_mul_f32_e32 v218, v96, v212
	v_mul_f32_e32 v219, v97, v212
	v_mul_f32_e32 v220, v98, v212
	v_mul_f32_e32 v221, v99, v212
	v_mul_f32_e32 v222, v88, v212
	v_mul_f32_e32 v223, v89, v212
	v_mul_f32_e32 v224, v90, v212
	v_mul_f32_e32 v225, v91, v212
	v_exp_f32_e32 v218, v218
	v_exp_f32_e32 v219, v219
	v_exp_f32_e32 v220, v220
	v_exp_f32_e32 v221, v221
	v_exp_f32_e32 v222, v222
	v_exp_f32_e32 v223, v223
	v_exp_f32_e32 v224, v224
	v_exp_f32_e32 v225, v225
	s_mov_b32 s100, 0x2c000
	v_lshl_add_u64 v[228:229], v[226:227], 0, s[100:101]
	v_fma_f32 v218, v218, v204, v204
	v_fma_f32 v219, v219, v204, v204
	v_fma_f32 v220, v220, v204, v204
	v_fma_f32 v221, v221, v204, v204
	v_fma_f32 v222, v222, v204, v204
	v_fma_f32 v223, v223, v204, v204
	v_fma_f32 v224, v224, v204, v204
	v_fma_f32 v225, v225, v204, v204
	v_rcp_f32_e32 v218, v218
	v_rcp_f32_e32 v219, v219
	v_rcp_f32_e32 v220, v220
	v_rcp_f32_e32 v221, v221
	v_rcp_f32_e32 v222, v222
	v_rcp_f32_e32 v223, v223
	v_rcp_f32_e32 v224, v224
	v_rcp_f32_e32 v225, v225
	s_nop 0
	v_mul_f32_e32 v92, v92, v218
	v_mul_f32_e32 v93, v93, v219
	v_mul_f32_e32 v94, v94, v220
	v_mul_f32_e32 v95, v95, v221
	v_mul_f32_e32 v84, v84, v222
	v_mul_f32_e32 v85, v85, v223
	v_mul_f32_e32 v86, v86, v224
	v_mul_f32_e32 v87, v87, v225
	v_cvt_pk_bf16_f32 v88, v92, v93
	v_cvt_pk_bf16_f32 v89, v94, v95
	v_cvt_pk_bf16_f32 v90, v84, v85
	v_cvt_pk_bf16_f32 v91, v86, v87
	global_store_dwordx4 v[228:229], v[88:91], off
	v_mul_f32_e32 v218, v80, v213
	v_mul_f32_e32 v219, v81, v213
	v_mul_f32_e32 v220, v82, v213
	v_mul_f32_e32 v221, v83, v213
	v_mul_f32_e32 v222, v72, v213
	v_mul_f32_e32 v223, v73, v213
	v_mul_f32_e32 v224, v74, v213
	v_mul_f32_e32 v225, v75, v213
	v_exp_f32_e32 v218, v218
	v_exp_f32_e32 v219, v219
	v_exp_f32_e32 v220, v220
	v_exp_f32_e32 v221, v221
	v_exp_f32_e32 v222, v222
	v_exp_f32_e32 v223, v223
	v_exp_f32_e32 v224, v224
	v_exp_f32_e32 v225, v225
	s_mov_b32 s100, 0x42000
	v_lshl_add_u64 v[228:229], v[226:227], 0, s[100:101]
	v_fma_f32 v218, v218, v205, v205
	v_fma_f32 v219, v219, v205, v205
	v_fma_f32 v220, v220, v205, v205
	v_fma_f32 v221, v221, v205, v205
	v_fma_f32 v222, v222, v205, v205
	v_fma_f32 v223, v223, v205, v205
	v_fma_f32 v224, v224, v205, v205
	v_fma_f32 v225, v225, v205, v205
	v_rcp_f32_e32 v218, v218
	v_rcp_f32_e32 v219, v219
	v_rcp_f32_e32 v220, v220
	v_rcp_f32_e32 v221, v221
	v_rcp_f32_e32 v222, v222
	v_rcp_f32_e32 v223, v223
	v_rcp_f32_e32 v224, v224
	v_rcp_f32_e32 v225, v225
	s_nop 0
	v_mul_f32_e32 v76, v76, v218
	v_mul_f32_e32 v77, v77, v219
	v_mul_f32_e32 v78, v78, v220
	v_mul_f32_e32 v79, v79, v221
	v_mul_f32_e32 v68, v68, v222
	v_mul_f32_e32 v69, v69, v223
	v_mul_f32_e32 v70, v70, v224
	v_mul_f32_e32 v71, v71, v225
	v_cvt_pk_bf16_f32 v72, v76, v77
	v_cvt_pk_bf16_f32 v73, v78, v79
	v_cvt_pk_bf16_f32 v74, v68, v69
; __device__ __forceinline__ unsigned cvtpk(float lo, float hi) { f32x2 v = {lo, hi}; bf16x2_t b = __builtin_convertvector(v, bf16x2_t); return __builtin_bit_cast(unsigned, b); }
; #define PG8_BAR __builtin_amdgcn_s_barrier()
;     __device__ __forceinline__ void operator()(const f32x4 (&acc)[2][2][4][2], const Unit& u, int wr, int wc, int fr, int fq) const {
;     ...
;                     for (int i = 0; i < 4; ++i) {
;                         const float ag = acc[ai][0][m][n][i];
;                         const float e = __builtin_amdgcn_exp2f(ag * nml);
;                         hv[4 * n + i] = (ag * acc[ai][1][m][n][i]) * (mul2 * __builtin_amdgcn_rcpf(1.0f + e));
;                     }
;                 u32x4 w; w.x = cvtpk(hv[0], hv[1]); w.y = cvtpk(hv[2], hv[3]); w.z = cvtpk(hv[4], hv[5]); w.w = cvtpk(hv[6], hv[7]);
;                 *(u32x4*)(H + (size_t)(row0 + ai * HALF + m * 16) * 2816 + col0) = w;
; template <class Epi, class Sched, bool ALIGN_EPI = false, bool SP2 = false>
; __device__ __forceinline__ void gemm_phase(PG8_LAS unsigned char* lds, const Gemm g, const Sched& S, const Epi& E) {
;     ...
;         if (!has_next) break;
; #pragma unroll
;         for (int a = 0; a < 2; ++a)
; #pragma unroll
;             for (int b = 0; b < 2; ++b)
; #pragma unroll
;                 for (int m = 0; m < 4; ++m)
; #pragma unroll
;                     for (int n = 0; n < 2; ++n) acc[a][b][m][n] = (f32x4){0.f, 0.f, 0.f, 0.f};
;         cur = nxt; cA = nA; cB = nB; ++ui;
;         if constexpr (ALIGN_EPI) { if (wr == 1) PG8_BAR; }
	v_cvt_pk_bf16_f32 v75, v70, v71
	global_store_dwordx4 v[228:229], v[72:75], off
	v_mul_f32_e32 v218, v64, v214
	v_mul_f32_e32 v219, v65, v214
	v_mul_f32_e32 v220, v66, v214
	v_mul_f32_e32 v221, v67, v214
	v_mul_f32_e32 v222, v56, v214
	v_mul_f32_e32 v223, v57, v214
	v_mul_f32_e32 v224, v58, v214
	v_mul_f32_e32 v225, v59, v214
	v_exp_f32_e32 v218, v218
	v_exp_f32_e32 v219, v219
	v_exp_f32_e32 v220, v220
	v_exp_f32_e32 v221, v221
	v_exp_f32_e32 v222, v222
	v_exp_f32_e32 v223, v223
	v_exp_f32_e32 v224, v224
	v_exp_f32_e32 v225, v225
	s_mov_b32 s100, 0xb0000
	v_lshl_add_u64 v[228:229], v[226:227], 0, s[100:101]
	v_fma_f32 v218, v218, v206, v206
	v_fma_f32 v219, v219, v206, v206
	v_fma_f32 v220, v220, v206, v206
	v_fma_f32 v221, v221, v206, v206
	v_fma_f32 v222, v222, v206, v206
	v_fma_f32 v223, v223, v206, v206
	v_fma_f32 v224, v224, v206, v206
	v_fma_f32 v225, v225, v206, v206
	v_rcp_f32_e32 v218, v218
	v_rcp_f32_e32 v219, v219
	v_rcp_f32_e32 v220, v220
	v_rcp_f32_e32 v221, v221
	v_rcp_f32_e32 v222, v222
	v_rcp_f32_e32 v223, v223
	v_rcp_f32_e32 v224, v224
	v_rcp_f32_e32 v225, v225
	s_nop 0
	v_mul_f32_e32 v60, v60, v218
	v_mul_f32_e32 v61, v61, v219
	v_mul_f32_e32 v62, v62, v220
	v_mul_f32_e32 v63, v63, v221
	v_mul_f32_e32 v52, v52, v222
	v_mul_f32_e32 v53, v53, v223
	v_mul_f32_e32 v54, v54, v224
	v_mul_f32_e32 v55, v55, v225
	v_cvt_pk_bf16_f32 v56, v60, v61
	v_cvt_pk_bf16_f32 v57, v62, v63
	v_cvt_pk_bf16_f32 v58, v52, v53
	v_cvt_pk_bf16_f32 v59, v54, v55
	global_store_dwordx4 v[228:229], v[56:59], off
	v_mul_f32_e32 v218, v48, v215
	v_mul_f32_e32 v219, v49, v215
	v_mul_f32_e32 v220, v50, v215
	v_mul_f32_e32 v221, v51, v215
	v_mul_f32_e32 v222, v40, v215
	v_mul_f32_e32 v223, v41, v215
	v_mul_f32_e32 v224, v42, v215
	v_mul_f32_e32 v225, v43, v215
	v_exp_f32_e32 v218, v218
	v_exp_f32_e32 v219, v219
	v_exp_f32_e32 v220, v220
	v_exp_f32_e32 v221, v221
	v_exp_f32_e32 v222, v222
	v_exp_f32_e32 v223, v223
	v_exp_f32_e32 v224, v224
	v_exp_f32_e32 v225, v225
	s_mov_b32 s100, 0xc6000
	v_lshl_add_u64 v[228:229], v[226:227], 0, s[100:101]
	v_fma_f32 v218, v218, v207, v207
	v_fma_f32 v219, v219, v207, v207
	v_fma_f32 v220, v220, v207, v207
	v_fma_f32 v221, v221, v207, v207
	v_fma_f32 v222, v222, v207, v207
	v_fma_f32 v223, v223, v207, v207
	v_fma_f32 v224, v224, v207, v207
	v_fma_f32 v225, v225, v207, v207
	v_rcp_f32_e32 v218, v218
	v_rcp_f32_e32 v219, v219
	v_rcp_f32_e32 v220, v220
	v_rcp_f32_e32 v221, v221
	v_rcp_f32_e32 v222, v222
	v_rcp_f32_e32 v223, v223
	v_rcp_f32_e32 v224, v224
	v_rcp_f32_e32 v225, v225
	s_nop 0
	v_mul_f32_e32 v44, v44, v218
	v_mul_f32_e32 v45, v45, v219
	v_mul_f32_e32 v46, v46, v220
	v_mul_f32_e32 v47, v47, v221
	v_mul_f32_e32 v36, v36, v222
	v_mul_f32_e32 v37, v37, v223
	v_mul_f32_e32 v38, v38, v224
	v_mul_f32_e32 v39, v39, v225
	v_cvt_pk_bf16_f32 v40, v44, v45
	v_cvt_pk_bf16_f32 v41, v46, v47
	v_cvt_pk_bf16_f32 v42, v36, v37
	v_cvt_pk_bf16_f32 v43, v38, v39
	global_store_dwordx4 v[228:229], v[40:43], off
	v_mul_f32_e32 v218, v32, v216
	v_mul_f32_e32 v219, v33, v216
	v_mul_f32_e32 v220, v34, v216
	v_mul_f32_e32 v221, v35, v216
	v_mul_f32_e32 v222, v24, v216
	v_mul_f32_e32 v223, v25, v216
	v_mul_f32_e32 v224, v26, v216
	v_mul_f32_e32 v225, v27, v216
	v_exp_f32_e32 v218, v218
	v_exp_f32_e32 v219, v219
	v_exp_f32_e32 v220, v220
	v_exp_f32_e32 v221, v221
	v_exp_f32_e32 v222, v222
	v_exp_f32_e32 v223, v223
	v_exp_f32_e32 v224, v224
	v_exp_f32_e32 v225, v225
	s_mov_b32 s100, 0xdc000
	v_lshl_add_u64 v[228:229], v[226:227], 0, s[100:101]
	v_fma_f32 v218, v218, v208, v208
	v_fma_f32 v219, v219, v208, v208
	v_fma_f32 v220, v220, v208, v208
	v_fma_f32 v221, v221, v208, v208
	v_fma_f32 v222, v222, v208, v208
	v_fma_f32 v223, v223, v208, v208
	v_fma_f32 v224, v224, v208, v208
	v_fma_f32 v225, v225, v208, v208
	v_rcp_f32_e32 v218, v218
	v_rcp_f32_e32 v219, v219
	v_rcp_f32_e32 v220, v220
	v_rcp_f32_e32 v221, v221
	v_rcp_f32_e32 v222, v222
	v_rcp_f32_e32 v223, v223
	v_rcp_f32_e32 v224, v224
	v_rcp_f32_e32 v225, v225
	s_nop 0
	v_mul_f32_e32 v28, v28, v218
	v_mul_f32_e32 v29, v29, v219
	v_mul_f32_e32 v30, v30, v220
	v_mul_f32_e32 v31, v31, v221
	v_mul_f32_e32 v20, v20, v222
	v_mul_f32_e32 v21, v21, v223
	v_mul_f32_e32 v22, v22, v224
	v_mul_f32_e32 v23, v23, v225
	v_cvt_pk_bf16_f32 v24, v28, v29
	v_cvt_pk_bf16_f32 v25, v30, v31
	v_cvt_pk_bf16_f32 v26, v20, v21
	v_cvt_pk_bf16_f32 v27, v22, v23
	global_store_dwordx4 v[228:229], v[24:27], off
	v_mul_f32_e32 v218, v16, v217
	v_mul_f32_e32 v219, v17, v217
	v_mul_f32_e32 v220, v18, v217
	v_mul_f32_e32 v221, v19, v217
	v_mul_f32_e32 v222, v8, v217
	v_mul_f32_e32 v223, v9, v217
	v_mul_f32_e32 v224, v10, v217
	v_mul_f32_e32 v225, v11, v217
	v_exp_f32_e32 v218, v218
	v_exp_f32_e32 v219, v219
	v_exp_f32_e32 v220, v220
	v_exp_f32_e32 v221, v221
	v_exp_f32_e32 v222, v222
	v_exp_f32_e32 v223, v223
	v_exp_f32_e32 v224, v224
	v_exp_f32_e32 v225, v225
	s_mov_b32 s100, 0xf2000
	v_lshl_add_u64 v[228:229], v[226:227], 0, s[100:101]
	v_fma_f32 v218, v218, v209, v209
	v_fma_f32 v219, v219, v209, v209
	v_fma_f32 v220, v220, v209, v209
	v_fma_f32 v221, v221, v209, v209
	v_fma_f32 v222, v222, v209, v209
	v_fma_f32 v223, v223, v209, v209
	v_fma_f32 v224, v224, v209, v209
	v_fma_f32 v225, v225, v209, v209
	v_rcp_f32_e32 v218, v218
	v_rcp_f32_e32 v219, v219
	v_rcp_f32_e32 v220, v220
	v_rcp_f32_e32 v221, v221
	v_rcp_f32_e32 v222, v222
	v_rcp_f32_e32 v223, v223
	v_rcp_f32_e32 v224, v224
	v_rcp_f32_e32 v225, v225
	s_nop 0
	v_mul_f32_e32 v12, v12, v218
	v_mul_f32_e32 v13, v13, v219
	v_mul_f32_e32 v14, v14, v220
	v_mul_f32_e32 v15, v15, v221
	v_mul_f32_e32 v4, v4, v222
	v_mul_f32_e32 v5, v5, v223
	v_mul_f32_e32 v6, v6, v224
	v_mul_f32_e32 v7, v7, v225
	v_cvt_pk_bf16_f32 v8, v12, v13
	v_cvt_pk_bf16_f32 v9, v14, v15
	v_cvt_pk_bf16_f32 v10, v4, v5
	v_cvt_pk_bf16_f32 v11, v6, v7
	global_store_dwordx4 v[228:229], v[8:11], off
	s_andn2_b64 vcc, exec, s[4:5]
	s_mov_b64 s[4:5], -1
	s_cbranch_vccnz .LBB0_401
	s_andn2_b64 vcc, exec, s[10:11]
	s_cbranch_vccnz .LBB0_400
	s_barrier
	s_branch .LBB0_400

; __device__ __forceinline__ unsigned cvtpk(float lo, float hi) { f32x2 v = {lo, hi}; bf16x2_t b = __builtin_convertvector(v, bf16x2_t); return __builtin_bit_cast(unsigned, b); }
;     __device__ __forceinline__ void operator()(const f32x4 (&acc)[2][2][4][2], const Unit& u, int wr, int wc, int fr, int fq) const {
;     ...
;                 for (int bj = 0; bj < 2; ++bj) w[ai][m][bj] = *(const u32x4*)(xb + (size_t)(row0 + ai * HALF + m * 16) * 1024 + col0 + bj * HALF);
; #pragma unroll
;         for (int ai = 0; ai < 2; ++ai)
; #pragma unroll
;             for (int m = 0; m < 4; ++m) {
;                 const int row = row0 + ai * HALF + m * 16;
;                 const size_t off = (size_t)row * 1024 + col0;
;                 float ss = 0.f;
; #pragma unroll
;                 for (int bj = 0; bj < 2; ++bj) {
;                     const u32x4 wv = w[ai][m][bj];
;                     f32x4 o0 = acc[ai][bj][m][0], o1 = acc[ai][bj][m][1];
;                     o0[0] += __builtin_bit_cast(float, wv.x << 16); o0[1] += __builtin_bit_cast(float, wv.x & 0xffff0000u); o0[2] += __builtin_bit_cast(float, wv.y << 16); o0[3] += __builtin_bit_cast(float, wv.y & 0xffff0000u);
;                     o1[0] += __builtin_bit_cast(float, wv.z << 16); o1[1] += __builtin_bit_cast(float, wv.z & 0xffff0000u); o1[2] += __builtin_bit_cast(float, wv.w << 16); o1[3] += __builtin_bit_cast(float, wv.w & 0xffff0000u);
;                     if (last) { *(f32x4*)(out + off + bj * HALF) = o0; *(f32x4*)(out + off + bj * HALF + 4) = o1; }
;                     else {
;                         u32x4 v; v.x = cvtpk(o0[0], o0[1]); v.y = cvtpk(o0[2], o0[3]); v.z = cvtpk(o1[0], o1[1]); v.w = cvtpk(o1[2], o1[3]);
;                         *(u32x4*)(xb + off + bj * HALF) = v;
;                         ss += (o0[0] * o0[0] + o0[1] * o0[1]) + (o0[2] * o0[2] + o0[3] * o0[3]) + (o1[0] * o1[0] + o1[1] * o1[1]) + (o1[2] * o1[2] + o1[3] * o1[3]);
.LBB0_483:
	s_and_b64 vcc, exec, s[10:11]
	s_cbranch_vccz .Lrd_last
	v_lshl_add_u32 v208, s3, 8, v3
	v_lshl_or_b32 v209, s52, 8, v235
	v_lshlrev_b32_e32 v238, 1, v209
	v_lshl_add_u32 v238, v208, 11, v238
	v_mov_b32_e32 v239, v2
	s_mov_b32 s101, 0
	s_mov_b32 s28, 0xffff0000
	v_lshl_add_u64 v[210:211], s[18:19], 0, v[238:239]
	global_load_dwordx4 v[230:233], v[210:211], off
	global_load_dwordx4 v[188:191], v[210:211], off offset:256
	s_mov_b32 s100, 0x8000
	v_lshl_add_u64 v[212:213], v[210:211], 0, s[100:101]
	global_load_dwordx4 v[184:187], v[212:213], off
	global_load_dwordx4 v[180:183], v[212:213], off offset:256
	s_mov_b32 s100, 0x10000
	v_lshl_add_u64 v[214:215], v[210:211], 0, s[100:101]
	global_load_dwordx4 v[176:179], v[214:215], off
	global_load_dwordx4 v[172:175], v[214:215], off offset:256
	s_mov_b32 s100, 0x18000
	v_lshl_add_u64 v[216:217], v[210:211], 0, s[100:101]
	global_load_dwordx4 v[168:171], v[216:217], off
	global_load_dwordx4 v[156:159], v[216:217], off offset:256
	s_mov_b32 s100, 0x40000
	v_lshl_add_u64 v[218:219], v[210:211], 0, s[100:101]
	global_load_dwordx4 v[144:147], v[218:219], off
	global_load_dwordx4 v[132:135], v[218:219], off offset:256
	s_mov_b32 s100, 0x48000
	v_lshl_add_u64 v[220:221], v[210:211], 0, s[100:101]
	global_load_dwordx4 v[120:123], v[220:221], off
	global_load_dwordx4 v[112:115], v[220:221], off offset:256
	s_mov_b32 s100, 0x50000
	v_lshl_add_u64 v[222:223], v[210:211], 0, s[100:101]
	global_load_dwordx4 v[100:103], v[222:223], off
	global_load_dwordx4 v[92:95], v[222:223], off offset:256
	s_mov_b32 s100, 0x58000
	v_lshl_add_u64 v[224:225], v[210:211], 0, s[100:101]
	global_load_dwordx4 v[80:83], v[224:225], off
	global_load_dwordx4 v[68:71], v[224:225], off offset:256
	s_waitcnt vmcnt(14)
	v_lshlrev_b32_e32 v238, 16, v230
	v_and_b32_e32 v239, s28, v230
	v_lshlrev_b32_e32 v240, 16, v231
	v_and_b32_e32 v241, s28, v231
	v_lshlrev_b32_e32 v242, 16, v232
	v_and_b32_e32 v243, s28, v232
	v_lshlrev_b32_e32 v198, 16, v233
	v_and_b32_e32 v199, s28, v233
	v_add_f32_e32 v164, v164, v238
	v_add_f32_e32 v165, v165, v239
	v_add_f32_e32 v166, v166, v240
	v_add_f32_e32 v167, v167, v241
	v_add_f32_e32 v160, v160, v242
	v_add_f32_e32 v161, v161, v243
	v_add_f32_e32 v162, v162, v198
	v_add_f32_e32 v163, v163, v199
	v_cvt_pk_bf16_f32 v230, v164, v165
	v_cvt_pk_bf16_f32 v231, v166, v167
	v_cvt_pk_bf16_f32 v232, v160, v161
	v_cvt_pk_bf16_f32 v233, v162, v163
	global_store_dwordx4 v[210:211], v[230:233], off
	v_lshlrev_b32_e32 v238, 16, v188
	v_and_b32_e32 v239, s28, v188
	v_lshlrev_b32_e32 v240, 16, v189
	v_and_b32_e32 v241, s28, v189
	v_lshlrev_b32_e32 v242, 16, v190
	v_and_b32_e32 v243, s28, v190
	v_lshlrev_b32_e32 v198, 16, v191
	v_and_b32_e32 v199, s28, v191
	v_add_f32_e32 v152, v152, v238
	v_add_f32_e32 v153, v153, v239
	v_add_f32_e32 v154, v154, v240
	v_add_f32_e32 v155, v155, v241
	v_add_f32_e32 v148, v148, v242
	v_add_f32_e32 v149, v149, v243
	v_add_f32_e32 v150, v150, v198
	v_add_f32_e32 v151, v151, v199
	v_cvt_pk_bf16_f32 v188, v152, v153
	v_cvt_pk_bf16_f32 v189, v154, v155
	v_cvt_pk_bf16_f32 v190, v148, v149
	v_cvt_pk_bf16_f32 v191, v150, v151
	global_store_dwordx4 v[210:211], v[188:191], off offset:256
	v_mul_f32_e32 v238, v164, v164
	v_mul_f32_e32 v239, v165, v165
	v_mul_f32_e32 v240, v166, v166
	v_mul_f32_e32 v241, v167, v167
	v_fma_f32 v238, v160, v160, v238
	v_fma_f32 v239, v161, v161, v239
	v_fma_f32 v240, v162, v162, v240
	v_fma_f32 v241, v163, v163, v241
	v_fma_f32 v238, v152, v152, v238
	v_fma_f32 v239, v153, v153, v239
	v_fma_f32 v240, v154, v154, v240
	v_fma_f32 v241, v155, v155, v241
	v_fma_f32 v238, v148, v148, v238
	v_fma_f32 v239, v149, v149, v239
	v_fma_f32 v240, v150, v150, v240
	v_fma_f32 v241, v151, v151, v241
	v_add_f32_e32 v238, v238, v240
	v_add_f32_e32 v239, v239, v241
	v_add_f32_e32 v210, v238, v239
	s_waitcnt vmcnt(14)
	v_lshlrev_b32_e32 v238, 16, v184
	v_and_b32_e32 v239, s28, v184
	v_lshlrev_b32_e32 v240, 16, v185
	v_and_b32_e32 v241, s28, v185
	v_lshlrev_b32_e32 v242, 16, v186
	v_and_b32_e32 v243, s28, v186
	v_lshlrev_b32_e32 v198, 16, v187
	v_and_b32_e32 v199, s28, v187
	v_add_f32_e32 v140, v140, v238
	v_add_f32_e32 v141, v141, v239
	v_add_f32_e32 v142, v142, v240
	v_add_f32_e32 v143, v143, v241
	v_add_f32_e32 v136, v136, v242
	v_add_f32_e32 v137, v137, v243
	v_add_f32_e32 v138, v138, v198
	v_add_f32_e32 v139, v139, v199
	v_cvt_pk_bf16_f32 v184, v140, v141
	v_cvt_pk_bf16_f32 v185, v142, v143
	v_cvt_pk_bf16_f32 v186, v136, v137
	v_cvt_pk_bf16_f32 v187, v138, v139
	global_store_dwordx4 v[212:213], v[184:187], off
	v_lshlrev_b32_e32 v238, 16, v180
	v_and_b32_e32 v239, s28, v180
	v_lshlrev_b32_e32 v240, 16, v181
	v_and_b32_e32 v241, s28, v181
	v_lshlrev_b32_e32 v242, 16, v182
	v_and_b32_e32 v243, s28, v182
	v_lshlrev_b32_e32 v198, 16, v183
	v_and_b32_e32 v199, s28, v183
	v_add_f32_e32 v128, v128, v238
	v_add_f32_e32 v129, v129, v239
	v_add_f32_e32 v130, v130, v240
	v_add_f32_e32 v131, v131, v241
	v_add_f32_e32 v124, v124, v242
	v_add_f32_e32 v125, v125, v243
	v_add_f32_e32 v126, v126, v198
	v_add_f32_e32 v127, v127, v199
	v_cvt_pk_bf16_f32 v180, v128, v129
	v_cvt_pk_bf16_f32 v181, v130, v131
	v_cvt_pk_bf16_f32 v182, v124, v125
	v_cvt_pk_bf16_f32 v183, v126, v127
	global_store_dwordx4 v[212:213], v[180:183], off offset:256
	v_mul_f32_e32 v238, v140, v140
	v_mul_f32_e32 v239, v141, v141
	v_mul_f32_e32 v240, v142, v142
	v_mul_f32_e32 v241, v143, v143
	v_fma_f32 v238, v136, v136, v238
	v_fma_f32 v239, v137, v137, v239
	v_fma_f32 v240, v138, v138, v240
	v_fma_f32 v241, v139, v139, v241
	v_fma_f32 v238, v128, v128, v238
	v_fma_f32 v239, v129, v129, v239
	v_fma_f32 v240, v130, v130, v240
	v_fma_f32 v241, v131, v131, v241
	v_fma_f32 v238, v124, v124, v238
	v_fma_f32 v239, v125, v125, v239
	v_fma_f32 v240, v126, v126, v240
	v_fma_f32 v241, v127, v127, v241
	v_add_f32_e32 v238, v238, v240
	v_add_f32_e32 v239, v239, v241
	v_add_f32_e32 v212, v238, v239
	s_waitcnt vmcnt(14)
; __device__ __forceinline__ unsigned cvtpk(float lo, float hi) { f32x2 v = {lo, hi}; bf16x2_t b = __builtin_convertvector(v, bf16x2_t); return __builtin_bit_cast(unsigned, b); }
;     __device__ __forceinline__ void operator()(const f32x4 (&acc)[2][2][4][2], const Unit& u, int wr, int wc, int fr, int fq) const {
;     ...
;                 for (int bj = 0; bj < 2; ++bj) {
;                     const u32x4 wv = w[ai][m][bj];
;                     f32x4 o0 = acc[ai][bj][m][0], o1 = acc[ai][bj][m][1];
;                     o0[0] += __builtin_bit_cast(float, wv.x << 16); o0[1] += __builtin_bit_cast(float, wv.x & 0xffff0000u); o0[2] += __builtin_bit_cast(float, wv.y << 16); o0[3] += __builtin_bit_cast(float, wv.y & 0xffff0000u);
;                     o1[0] += __builtin_bit_cast(float, wv.z << 16); o1[1] += __builtin_bit_cast(float, wv.z & 0xffff0000u); o1[2] += __builtin_bit_cast(float, wv.w << 16); o1[3] += __builtin_bit_cast(float, wv.w & 0xffff0000u);
;                     if (last) { *(f32x4*)(out + off + bj * HALF) = o0; *(f32x4*)(out + off + bj * HALF + 4) = o1; }
;                     else {
;                         u32x4 v; v.x = cvtpk(o0[0], o0[1]); v.y = cvtpk(o0[2], o0[3]); v.z = cvtpk(o1[0], o1[1]); v.w = cvtpk(o1[2], o1[3]);
;                         *(u32x4*)(xb + off + bj * HALF) = v;
;                         ss += (o0[0] * o0[0] + o0[1] * o0[1]) + (o0[2] * o0[2] + o0[3] * o0[3]) + (o1[0] * o1[0] + o1[1] * o1[1]) + (o1[2] * o1[2] + o1[3] * o1[3]);
	v_lshlrev_b32_e32 v238, 16, v176
	v_and_b32_e32 v239, s28, v176
	v_lshlrev_b32_e32 v240, 16, v177
	v_and_b32_e32 v241, s28, v177
	v_lshlrev_b32_e32 v242, 16, v178
	v_and_b32_e32 v243, s28, v178
	v_lshlrev_b32_e32 v198, 16, v179
	v_and_b32_e32 v199, s28, v179
	v_add_f32_e32 v116, v116, v238
	v_add_f32_e32 v117, v117, v239
	v_add_f32_e32 v118, v118, v240
	v_add_f32_e32 v119, v119, v241
	v_add_f32_e32 v108, v108, v242
	v_add_f32_e32 v109, v109, v243
	v_add_f32_e32 v110, v110, v198
	v_add_f32_e32 v111, v111, v199
	v_cvt_pk_bf16_f32 v176, v116, v117
	v_cvt_pk_bf16_f32 v177, v118, v119
	v_cvt_pk_bf16_f32 v178, v108, v109
	v_cvt_pk_bf16_f32 v179, v110, v111
	global_store_dwordx4 v[214:215], v[176:179], off
	v_lshlrev_b32_e32 v238, 16, v172
	v_and_b32_e32 v239, s28, v172
	v_lshlrev_b32_e32 v240, 16, v173
	v_and_b32_e32 v241, s28, v173
	v_lshlrev_b32_e32 v242, 16, v174
	v_and_b32_e32 v243, s28, v174
	v_lshlrev_b32_e32 v198, 16, v175
	v_and_b32_e32 v199, s28, v175
	v_add_f32_e32 v104, v104, v238
	v_add_f32_e32 v105, v105, v239
	v_add_f32_e32 v106, v106, v240
	v_add_f32_e32 v107, v107, v241
	v_add_f32_e32 v96, v96, v242
	v_add_f32_e32 v97, v97, v243
	v_add_f32_e32 v98, v98, v198
	v_add_f32_e32 v99, v99, v199
	v_cvt_pk_bf16_f32 v172, v104, v105
	v_cvt_pk_bf16_f32 v173, v106, v107
	v_cvt_pk_bf16_f32 v174, v96, v97
	v_cvt_pk_bf16_f32 v175, v98, v99
	global_store_dwordx4 v[214:215], v[172:175], off offset:256
	v_mul_f32_e32 v238, v116, v116
	v_mul_f32_e32 v239, v117, v117
	v_mul_f32_e32 v240, v118, v118
	v_mul_f32_e32 v241, v119, v119
	v_fma_f32 v238, v108, v108, v238
	v_fma_f32 v239, v109, v109, v239
	v_fma_f32 v240, v110, v110, v240
	v_fma_f32 v241, v111, v111, v241
	v_fma_f32 v238, v104, v104, v238
	v_fma_f32 v239, v105, v105, v239
	v_fma_f32 v240, v106, v106, v240
	v_fma_f32 v241, v107, v107, v241
	v_fma_f32 v238, v96, v96, v238
	v_fma_f32 v239, v97, v97, v239
	v_fma_f32 v240, v98, v98, v240
	v_fma_f32 v241, v99, v99, v241
	v_add_f32_e32 v238, v238, v240
	v_add_f32_e32 v239, v239, v241
	v_add_f32_e32 v214, v238, v239
	s_waitcnt vmcnt(14)
	v_lshlrev_b32_e32 v238, 16, v168
	v_and_b32_e32 v239, s28, v168
	v_lshlrev_b32_e32 v240, 16, v169
	v_and_b32_e32 v241, s28, v169
	v_lshlrev_b32_e32 v242, 16, v170
	v_and_b32_e32 v243, s28, v170
	v_lshlrev_b32_e32 v198, 16, v171
	v_and_b32_e32 v199, s28, v171
	v_add_f32_e32 v88, v88, v238
	v_add_f32_e32 v89, v89, v239
	v_add_f32_e32 v90, v90, v240
	v_add_f32_e32 v91, v91, v241
	v_add_f32_e32 v84, v84, v242
	v_add_f32_e32 v85, v85, v243
	v_add_f32_e32 v86, v86, v198
	v_add_f32_e32 v87, v87, v199
	v_cvt_pk_bf16_f32 v168, v88, v89
	v_cvt_pk_bf16_f32 v169, v90, v91
	v_cvt_pk_bf16_f32 v170, v84, v85
	v_cvt_pk_bf16_f32 v171, v86, v87
	global_store_dwordx4 v[216:217], v[168:171], off
	v_lshlrev_b32_e32 v238, 16, v156
	v_and_b32_e32 v239, s28, v156
	v_lshlrev_b32_e32 v240, 16, v157
	v_and_b32_e32 v241, s28, v157
	v_lshlrev_b32_e32 v242, 16, v158
	v_and_b32_e32 v243, s28, v158
	v_lshlrev_b32_e32 v198, 16, v159
	v_and_b32_e32 v199, s28, v159
	v_add_f32_e32 v76, v76, v238
	v_add_f32_e32 v77, v77, v239
	v_add_f32_e32 v78, v78, v240
	v_add_f32_e32 v79, v79, v241
	v_add_f32_e32 v72, v72, v242
	v_add_f32_e32 v73, v73, v243
	v_add_f32_e32 v74, v74, v198
	v_add_f32_e32 v75, v75, v199
	v_cvt_pk_bf16_f32 v156, v76, v77
	v_cvt_pk_bf16_f32 v157, v78, v79
	v_cvt_pk_bf16_f32 v158, v72, v73
	v_cvt_pk_bf16_f32 v159, v74, v75
	global_store_dwordx4 v[216:217], v[156:159], off offset:256
	v_mul_f32_e32 v238, v88, v88
	v_mul_f32_e32 v239, v89, v89
	v_mul_f32_e32 v240, v90, v90
	v_mul_f32_e32 v241, v91, v91
	v_fma_f32 v238, v84, v84, v238
	v_fma_f32 v239, v85, v85, v239
	v_fma_f32 v240, v86, v86, v240
	v_fma_f32 v241, v87, v87, v241
	v_fma_f32 v238, v76, v76, v238
	v_fma_f32 v239, v77, v77, v239
	v_fma_f32 v240, v78, v78, v240
	v_fma_f32 v241, v79, v79, v241
	v_fma_f32 v238, v72, v72, v238
	v_fma_f32 v239, v73, v73, v239
	v_fma_f32 v240, v74, v74, v240
	v_fma_f32 v241, v75, v75, v241
	v_add_f32_e32 v238, v238, v240
	v_add_f32_e32 v239, v239, v241
	v_add_f32_e32 v216, v238, v239
	s_waitcnt vmcnt(14)
	v_lshlrev_b32_e32 v238, 16, v144
	v_and_b32_e32 v239, s28, v144
	v_lshlrev_b32_e32 v240, 16, v145
	v_and_b32_e32 v241, s28, v145
	v_lshlrev_b32_e32 v242, 16, v146
	v_and_b32_e32 v243, s28, v146
	v_lshlrev_b32_e32 v198, 16, v147
	v_and_b32_e32 v199, s28, v147
	v_add_f32_e32 v64, v64, v238
	v_add_f32_e32 v65, v65, v239
	v_add_f32_e32 v66, v66, v240
	v_add_f32_e32 v67, v67, v241
	v_add_f32_e32 v60, v60, v242
	v_add_f32_e32 v61, v61, v243
	v_add_f32_e32 v62, v62, v198
	v_add_f32_e32 v63, v63, v199
	v_cvt_pk_bf16_f32 v144, v64, v65
	v_cvt_pk_bf16_f32 v145, v66, v67
	v_cvt_pk_bf16_f32 v146, v60, v61
	v_cvt_pk_bf16_f32 v147, v62, v63
	global_store_dwordx4 v[218:219], v[144:147], off
	v_lshlrev_b32_e32 v238, 16, v132
	v_and_b32_e32 v239, s28, v132
	v_lshlrev_b32_e32 v240, 16, v133
	v_and_b32_e32 v241, s28, v133
	v_lshlrev_b32_e32 v242, 16, v134
	v_and_b32_e32 v243, s28, v134
	v_lshlrev_b32_e32 v198, 16, v135
	v_and_b32_e32 v199, s28, v135
	v_add_f32_e32 v56, v56, v238
	v_add_f32_e32 v57, v57, v239
	v_add_f32_e32 v58, v58, v240
	v_add_f32_e32 v59, v59, v241
	v_add_f32_e32 v52, v52, v242
	v_add_f32_e32 v53, v53, v243
	v_add_f32_e32 v54, v54, v198
	v_add_f32_e32 v55, v55, v199
	v_cvt_pk_bf16_f32 v132, v56, v57
	v_cvt_pk_bf16_f32 v133, v58, v59
	v_cvt_pk_bf16_f32 v134, v52, v53
	v_cvt_pk_bf16_f32 v135, v54, v55
	global_store_dwordx4 v[218:219], v[132:135], off offset:256
	v_mul_f32_e32 v238, v64, v64
	v_mul_f32_e32 v239, v65, v65
	v_mul_f32_e32 v240, v66, v66
	v_mul_f32_e32 v241, v67, v67
	v_fma_f32 v238, v60, v60, v238
	v_fma_f32 v239, v61, v61, v239
	v_fma_f32 v240, v62, v62, v240
	v_fma_f32 v241, v63, v63, v241
	v_fma_f32 v238, v56, v56, v238
	v_fma_f32 v239, v57, v57, v239
	v_fma_f32 v240, v58, v58, v240
	v_fma_f32 v241, v59, v59, v241
	v_fma_f32 v238, v52, v52, v238
	v_fma_f32 v239, v53, v53, v239
	v_fma_f32 v240, v54, v54, v240
	v_fma_f32 v241, v55, v55, v241
	v_add_f32_e32 v238, v238, v240
	v_add_f32_e32 v239, v239, v241
	v_add_f32_e32 v218, v238, v239
	s_waitcnt vmcnt(14)
; __device__ __forceinline__ unsigned cvtpk(float lo, float hi) { f32x2 v = {lo, hi}; bf16x2_t b = __builtin_convertvector(v, bf16x2_t); return __builtin_bit_cast(unsigned, b); }
;     __device__ __forceinline__ void operator()(const f32x4 (&acc)[2][2][4][2], const Unit& u, int wr, int wc, int fr, int fq) const {
;     ...
;                 for (int bj = 0; bj < 2; ++bj) {
;                     const u32x4 wv = w[ai][m][bj];
;                     f32x4 o0 = acc[ai][bj][m][0], o1 = acc[ai][bj][m][1];
;                     o0[0] += __builtin_bit_cast(float, wv.x << 16); o0[1] += __builtin_bit_cast(float, wv.x & 0xffff0000u); o0[2] += __builtin_bit_cast(float, wv.y << 16); o0[3] += __builtin_bit_cast(float, wv.y & 0xffff0000u);
;                     o1[0] += __builtin_bit_cast(float, wv.z << 16); o1[1] += __builtin_bit_cast(float, wv.z & 0xffff0000u); o1[2] += __builtin_bit_cast(float, wv.w << 16); o1[3] += __builtin_bit_cast(float, wv.w & 0xffff0000u);
;                     if (last) { *(f32x4*)(out + off + bj * HALF) = o0; *(f32x4*)(out + off + bj * HALF + 4) = o1; }
;                     else {
;                         u32x4 v; v.x = cvtpk(o0[0], o0[1]); v.y = cvtpk(o0[2], o0[3]); v.z = cvtpk(o1[0], o1[1]); v.w = cvtpk(o1[2], o1[3]);
;                         *(u32x4*)(xb + off + bj * HALF) = v;
;                         ss += (o0[0] * o0[0] + o0[1] * o0[1]) + (o0[2] * o0[2] + o0[3] * o0[3]) + (o1[0] * o1[0] + o1[1] * o1[1]) + (o1[2] * o1[2] + o1[3] * o1[3]);
;                     }
;                 }
;                 if (!last) {
;                     ss += __shfl_xor(ss, 16); ss += __shfl_xor(ss, 32);
;                     if (fq == 0) ssq_out[(size_t)row * 16 + 4 * u.pn + wc] = ss;
	v_lshlrev_b32_e32 v238, 16, v120
	v_and_b32_e32 v239, s28, v120
	v_lshlrev_b32_e32 v240, 16, v121
	v_and_b32_e32 v241, s28, v121
	v_lshlrev_b32_e32 v242, 16, v122
	v_and_b32_e32 v243, s28, v122
	v_lshlrev_b32_e32 v198, 16, v123
	v_and_b32_e32 v199, s28, v123
	v_add_f32_e32 v48, v48, v238
	v_add_f32_e32 v49, v49, v239
	v_add_f32_e32 v50, v50, v240
	v_add_f32_e32 v51, v51, v241
	v_add_f32_e32 v44, v44, v242
	v_add_f32_e32 v45, v45, v243
	v_add_f32_e32 v46, v46, v198
	v_add_f32_e32 v47, v47, v199
	v_cvt_pk_bf16_f32 v120, v48, v49
	v_cvt_pk_bf16_f32 v121, v50, v51
	v_cvt_pk_bf16_f32 v122, v44, v45
	v_cvt_pk_bf16_f32 v123, v46, v47
	global_store_dwordx4 v[220:221], v[120:123], off
	v_lshlrev_b32_e32 v238, 16, v112
	v_and_b32_e32 v239, s28, v112
	v_lshlrev_b32_e32 v240, 16, v113
	v_and_b32_e32 v241, s28, v113
	v_lshlrev_b32_e32 v242, 16, v114
	v_and_b32_e32 v243, s28, v114
	v_lshlrev_b32_e32 v198, 16, v115
	v_and_b32_e32 v199, s28, v115
	v_add_f32_e32 v40, v40, v238
	v_add_f32_e32 v41, v41, v239
	v_add_f32_e32 v42, v42, v240
	v_add_f32_e32 v43, v43, v241
	v_add_f32_e32 v36, v36, v242
	v_add_f32_e32 v37, v37, v243
	v_add_f32_e32 v38, v38, v198
	v_add_f32_e32 v39, v39, v199
	v_cvt_pk_bf16_f32 v112, v40, v41
	v_cvt_pk_bf16_f32 v113, v42, v43
	v_cvt_pk_bf16_f32 v114, v36, v37
	v_cvt_pk_bf16_f32 v115, v38, v39
	global_store_dwordx4 v[220:221], v[112:115], off offset:256
	v_mul_f32_e32 v238, v48, v48
	v_mul_f32_e32 v239, v49, v49
	v_mul_f32_e32 v240, v50, v50
	v_mul_f32_e32 v241, v51, v51
	v_fma_f32 v238, v44, v44, v238
	v_fma_f32 v239, v45, v45, v239
	v_fma_f32 v240, v46, v46, v240
	v_fma_f32 v241, v47, v47, v241
	v_fma_f32 v238, v40, v40, v238
	v_fma_f32 v239, v41, v41, v239
	v_fma_f32 v240, v42, v42, v240
	v_fma_f32 v241, v43, v43, v241
	v_fma_f32 v238, v36, v36, v238
	v_fma_f32 v239, v37, v37, v239
	v_fma_f32 v240, v38, v38, v240
	v_fma_f32 v241, v39, v39, v241
	v_add_f32_e32 v238, v238, v240
	v_add_f32_e32 v239, v239, v241
	v_add_f32_e32 v220, v238, v239
	s_waitcnt vmcnt(14)
	v_lshlrev_b32_e32 v238, 16, v100
	v_and_b32_e32 v239, s28, v100
	v_lshlrev_b32_e32 v240, 16, v101
	v_and_b32_e32 v241, s28, v101
	v_lshlrev_b32_e32 v242, 16, v102
	v_and_b32_e32 v243, s28, v102
	v_lshlrev_b32_e32 v198, 16, v103
	v_and_b32_e32 v199, s28, v103
	v_add_f32_e32 v32, v32, v238
	v_add_f32_e32 v33, v33, v239
	v_add_f32_e32 v34, v34, v240
	v_add_f32_e32 v35, v35, v241
	v_add_f32_e32 v28, v28, v242
	v_add_f32_e32 v29, v29, v243
	v_add_f32_e32 v30, v30, v198
	v_add_f32_e32 v31, v31, v199
	v_cvt_pk_bf16_f32 v100, v32, v33
	v_cvt_pk_bf16_f32 v101, v34, v35
	v_cvt_pk_bf16_f32 v102, v28, v29
	v_cvt_pk_bf16_f32 v103, v30, v31
	global_store_dwordx4 v[222:223], v[100:103], off
	v_lshlrev_b32_e32 v238, 16, v92
	v_and_b32_e32 v239, s28, v92
	v_lshlrev_b32_e32 v240, 16, v93
	v_and_b32_e32 v241, s28, v93
	v_lshlrev_b32_e32 v242, 16, v94
	v_and_b32_e32 v243, s28, v94
	v_lshlrev_b32_e32 v198, 16, v95
	v_and_b32_e32 v199, s28, v95
	v_add_f32_e32 v24, v24, v238
	v_add_f32_e32 v25, v25, v239
	v_add_f32_e32 v26, v26, v240
	v_add_f32_e32 v27, v27, v241
	v_add_f32_e32 v20, v20, v242
	v_add_f32_e32 v21, v21, v243
	v_add_f32_e32 v22, v22, v198
	v_add_f32_e32 v23, v23, v199
	v_cvt_pk_bf16_f32 v92, v24, v25
	v_cvt_pk_bf16_f32 v93, v26, v27
	v_cvt_pk_bf16_f32 v94, v20, v21
	v_cvt_pk_bf16_f32 v95, v22, v23
	global_store_dwordx4 v[222:223], v[92:95], off offset:256
	v_mul_f32_e32 v238, v32, v32
	v_mul_f32_e32 v239, v33, v33
	v_mul_f32_e32 v240, v34, v34
	v_mul_f32_e32 v241, v35, v35
	v_fma_f32 v238, v28, v28, v238
	v_fma_f32 v239, v29, v29, v239
	v_fma_f32 v240, v30, v30, v240
	v_fma_f32 v241, v31, v31, v241
	v_fma_f32 v238, v24, v24, v238
	v_fma_f32 v239, v25, v25, v239
	v_fma_f32 v240, v26, v26, v240
	v_fma_f32 v241, v27, v27, v241
	v_fma_f32 v238, v20, v20, v238
	v_fma_f32 v239, v21, v21, v239
	v_fma_f32 v240, v22, v22, v240
	v_fma_f32 v241, v23, v23, v241
	v_add_f32_e32 v238, v238, v240
	v_add_f32_e32 v239, v239, v241
	v_add_f32_e32 v222, v238, v239
	s_waitcnt vmcnt(14)
	v_lshlrev_b32_e32 v238, 16, v80
	v_and_b32_e32 v239, s28, v80
	v_lshlrev_b32_e32 v240, 16, v81
	v_and_b32_e32 v241, s28, v81
	v_lshlrev_b32_e32 v242, 16, v82
	v_and_b32_e32 v243, s28, v82
	v_lshlrev_b32_e32 v198, 16, v83
	v_and_b32_e32 v199, s28, v83
	v_add_f32_e32 v16, v16, v238
	v_add_f32_e32 v17, v17, v239
	v_add_f32_e32 v18, v18, v240
	v_add_f32_e32 v19, v19, v241
	v_add_f32_e32 v12, v12, v242
	v_add_f32_e32 v13, v13, v243
	v_add_f32_e32 v14, v14, v198
	v_add_f32_e32 v15, v15, v199
	v_cvt_pk_bf16_f32 v80, v16, v17
	v_cvt_pk_bf16_f32 v81, v18, v19
	v_cvt_pk_bf16_f32 v82, v12, v13
	v_cvt_pk_bf16_f32 v83, v14, v15
	global_store_dwordx4 v[224:225], v[80:83], off
	v_lshlrev_b32_e32 v238, 16, v68
	v_and_b32_e32 v239, s28, v68
	v_lshlrev_b32_e32 v240, 16, v69
	v_and_b32_e32 v241, s28, v69
	v_lshlrev_b32_e32 v242, 16, v70
	v_and_b32_e32 v243, s28, v70
	v_lshlrev_b32_e32 v198, 16, v71
	v_and_b32_e32 v199, s28, v71
	v_add_f32_e32 v8, v8, v238
	v_add_f32_e32 v9, v9, v239
	v_add_f32_e32 v10, v10, v240
	v_add_f32_e32 v11, v11, v241
	v_add_f32_e32 v4, v4, v242
	v_add_f32_e32 v5, v5, v243
	v_add_f32_e32 v6, v6, v198
	v_add_f32_e32 v7, v7, v199
	v_cvt_pk_bf16_f32 v68, v8, v9
	v_cvt_pk_bf16_f32 v69, v10, v11
	v_cvt_pk_bf16_f32 v70, v4, v5
	v_cvt_pk_bf16_f32 v71, v6, v7
	global_store_dwordx4 v[224:225], v[68:71], off offset:256
	v_mul_f32_e32 v238, v16, v16
	v_mul_f32_e32 v239, v17, v17
	v_mul_f32_e32 v240, v18, v18
	v_mul_f32_e32 v241, v19, v19
	v_fma_f32 v238, v12, v12, v238
	v_fma_f32 v239, v13, v13, v239
	v_fma_f32 v240, v14, v14, v240
	v_fma_f32 v241, v15, v15, v241
	v_fma_f32 v238, v8, v8, v238
	v_fma_f32 v239, v9, v9, v239
	v_fma_f32 v240, v10, v10, v240
	v_fma_f32 v241, v11, v11, v241
	v_fma_f32 v238, v4, v4, v238
	v_fma_f32 v239, v5, v5, v239
	v_fma_f32 v240, v6, v6, v240
	v_fma_f32 v241, v7, v7, v241
	v_add_f32_e32 v238, v238, v240
	v_add_f32_e32 v239, v239, v241
	v_add_f32_e32 v224, v238, v239
	s_nop 1
	v_permlane32_swap_b32_e32 v210, v212
	v_permlane32_swap_b32_e32 v214, v216
	v_permlane32_swap_b32_e32 v218, v220
	v_permlane32_swap_b32_e32 v222, v224
	v_add_f32_e32 v210, v210, v212
	v_add_f32_e32 v214, v214, v216
	v_add_f32_e32 v218, v218, v220
	v_add_f32_e32 v222, v222, v224
	s_nop 1
	v_permlane16_swap_b32_e32 v210, v214
	v_permlane16_swap_b32_e32 v218, v222
	v_add_f32_e32 v210, v210, v214
	v_add_f32_e32 v218, v218, v222
	v_bfe_u32 v238, v250, 4, 1
	v_bfe_u32 v239, v250, 5, 1
	v_lshl_or_b32 v238, v238, 1, v239
	v_lshlrev_b32_e32 v240, 6, v208
	v_lshl_add_u32 v240, v238, 10, v240
	s_lshl_b32 s29, s52, 4
	s_lshl_b32 s27, s46, 2
	s_add_i32 s29, s29, s27
	v_add_u32_e32 v240, s29, v240
	v_mov_b32_e32 v241, v2
	v_lshl_add_u64 v[240:241], s[14:15], 0, v[240:241]
	s_mov_b32 s100, 0x2000
	v_lshl_add_u64 v[242:243], v[240:241], 0, s[100:101]
	global_store_dword v[240:241], v210, off
	global_store_dword v[242:243], v218, off
	s_and_b64 vcc, exec, s[6:7]
	s_mov_b64 s[6:7], -1
	s_cbranch_vccnz .LBB0_468
	s_branch .LBB0_580
